# x15: as x14 with SGPR-base addressing for tile loads (no per-tile 64-bit VALU address math)
# speedup vs baseline: 1.0018x; 1.0018x over previous
; __device__ __forceinline__ int fresh_tid() { int t = threadIdx.x; asm volatile("" : "+v"(t)); return t; }
; __device__ __forceinline__ int v_st(int k, int c) { const int kk = (k & ~0xC) | ((k & 4) << 1) | ((k & 8) >> 1); return ((kk >> 3) * 4 + (c >> 5)) * 512 + ((kk & 7) * 32 + (c & 31)) * 2; }
; __device__ __forceinline__ int v_rd_base(int lane) { return ((lane & 3) << 3) | (((lane >> 2) & 3) << 6) | (((lane >> 4) & 1) << 5) | (((lane >> 5) & 1) << 8); }
; #define SLOAD(i, j) do { const long kr_ = KROW(j); sr_[i].vs0 = ld8(Vp + (kr_ + sr) * ldv + sc); sr_[i].ks0 = ld8(Kp + (kr_ + sr) * ldk + sc); \
;     if (DQK == 96) sr_[i].ks1 = ld8(Kp + (kr_ + sr2) * ldk + sc2); } while (0)
; #define SWRITE(b, i) do { *(bf16x8*)(V_lds + (b) * SHM_V + vst0) = sr_[i].vs0; *(bf16x8*)(K_lds + (b) * SHM_K + kst0) = sr_[i].ks0; \
;     if (DQK == 96) *(bf16x8*)(K_lds + (b) * SHM_K + kst1) = sr_[i].ks1; } while (0)
; template <int DQK, int MODE, int ldq, int ldk, int ldv> ...
;     ...
;   const int tid = fresh_tid(), wid = tid >> 6, lane = tid & 63, r32 = lane & 31, hi = lane >> 5;
;   char* V_lds = lds; char* K_lds = lds + 2 * SHM_V;
;   float* ws = (float*)(lds + 2 * SHM_V + 2 * SHM_K) + wid * 64; float* li_l = ws; float* al_l = ws + 32;
;   float m_reg = -1e30f, l_reg = 0; f32x16 o[2] = {}; bf16x8 qr[DQK / 16];
;   const bf16_t* Qw = Qb + (long)(wid * QBLK + r32) * ldq + hi * 8;
; #pragma unroll
;   for (int d0 = 0; d0 < DQK / 16; ++d0) qr[d0] = ld8(Qw + d0 * 16);
;   NaInfo na; na.brow = (const float*)(lds + rpb_off); na.qr = r0 + (wid >> 1); na.qc = (wid & 1) * 32 + r32;
;   const int sr = tid >> 3, sc = (tid & 7) * 8, vst0 = v_st(sr, sc), kst0 = KSWZ(sr, sc * 2);
;   const int sr2 = (tid & 255) >> 2, sc2 = 64 + (tid & 3) * 8, kst1 = KSWZ(sr2, sc2 * 2);
;   const int vb0 = (int)(uintptr_t)V_lds + v_rd_base(lane);
;   struct { bf16x8 vs0, ks0, ks1; } sr_[2];
;     ...
;   f32x16 pA0, pA1, pB0, pB1; float mnA, mnB, alA, alB; bf16x8 pa0, pa1, pa2, pa3;
;   constexpr int SE = 0, SO = 1;
;   SLOAD(SE, 0); SLOAD(SO, 1); asm volatile("s_waitcnt vmcnt(0)" ::: "memory"); SWRITE(0, SE); SWRITE(1, SO);
;   if (2 < NT) SLOAD(SE, 2);
;   __syncthreads();
.LBB0_299:
	v_readfirstlane_b32 s32, v234
	s_nop 0
	s_lshr_b32 s32, s32, 8
	s_ashr_i32 s11, s22, 7
	s_lshl_b32 s0, s22, 8
	s_lshl_b32 s10, s11, 13
	s_and_b32 s0, s0, 0x1f00
	s_or_b32 s6, s10, s0
	s_bfe_u32 s4, s22, 0x20005
	s_ashr_i32 s7, s6, 31
	s_mul_i32 s1, s6, 0x300
	s_mul_hi_i32 s0, s6, 0x300
	s_add_u32 s1, s16, s1
	s_addc_u32 s0, s17, s0
	s_mul_i32 s5, s4, 0xc0
	s_add_u32 s12, s1, s5
	s_addc_u32 s13, s0, 0
	s_add_u32 s0, s18, s5
	s_addc_u32 s1, s19, 0
	s_lshl_b32 s23, s4, 6
	s_lshl_b32 s4, s4, 7
	s_add_u32 s4, s20, s4
	s_addc_u32 s5, s21, 0
	s_lshl_b32 s24, s11, 8
	s_add_i32 s24, s24, 0x8000
	v_mov_b32_e32 v52, v234
	s_add_i32 s26, 0, 0x10000
	s_cmp_lg_u32 0, -1
	v_ashrrev_i32_e32 v130, 3, v52
	v_lshlrev_b32_e32 v28, 3, v52
	v_and_b32_e32 v0, 56, v28
	v_bfe_u32 v132, v52, 2, 6
	s_cselect_b32 s25, 0, 0
	s_ashr_i32 s11, s10, 31
	v_ashrrev_i32_e32 v131, 31, v130
	s_waitcnt lgkmcnt(0)
	v_lshlrev_b32_e32 v48, 1, v0
	v_lshl_add_u64 v[0:1], v[130:131], 0, s[10:11]
	v_mov_b64_e32 v[24:25], s[0:1]
	v_or_b32_e32 v8, s10, v132
	v_mad_u64_u32 v[4:5], s[28:29], v0, s70, v[24:25]
	v_mad_i64_i32 v[8:9], s[28:29], v8, s70, v[24:25]
	s_or_b32 s28, s10, 64
	s_ashr_i32 s29, s28, 31
	v_lshl_add_u64 v[16:17], v[130:131], 0, s[28:29]
	v_lshlrev_b64 v[2:3], 9, v[0:1]
	v_mad_u64_u32 v[18:19], s[30:31], v16, s70, v[24:25]
	v_lshl_add_u64 v[2:3], s[4:5], 0, v[2:3]
	v_mov_b32_e32 v49, v205
	v_mad_i32_i24 v5, v1, s70, v5
	v_mad_i32_i24 v19, v17, s70, v19
	v_lshlrev_b32_e32 v53, 4, v52
	v_lshl_add_u64 v[2:3], v[2:3], 0, v[48:49]
	v_lshl_add_u64 v[4:5], v[4:5], 0, v[48:49]
	v_lshlrev_b64 v[10:11], 9, v[16:17]
	v_lshl_add_u64 v[16:17], v[18:19], 0, v[48:49]
	v_or_b32_e32 v18, s28, v132
	v_and_b32_e32 v50, 48, v53
	global_load_dwordx4 v[0:3], v[2:3], off
	s_nop 0
	global_load_dwordx4 v[4:7], v[4:5], off
	v_mov_b32_e32 v51, v205
	v_lshl_add_u64 v[10:11], s[4:5], 0, v[10:11]
	v_mad_i64_i32 v[18:19], s[28:29], v18, s70, v[24:25]
	v_lshl_add_u64 v[8:9], v[8:9], 0, v[50:51]
	v_lshl_add_u64 v[12:13], v[10:11], 0, v[48:49]
	v_lshl_add_u64 v[20:21], v[18:19], 0, v[50:51]
	global_load_dwordx4 v[8:11], v[8:9], off offset:128
	s_nop 0
	global_load_dwordx4 v[12:15], v[12:13], off
	s_nop 0
	global_load_dwordx4 v[16:19], v[16:17], off
	s_nop 0
	global_load_dwordx4 v[20:23], v[20:21], off offset:128
	v_ashrrev_i32_e32 v54, 1, v52
	s_movk_i32 s11, 0xffe0
	v_bfe_u32 v133, v52, 5, 1
	v_bfi_b32 v29, s11, v54, v52
	v_mov_b64_e32 v[26:27], s[12:13]
	v_mad_i64_i32 v[26:27], s[12:13], v29, s70, v[26:27]
	v_lshlrev_b32_e32 v204, 4, v133
	v_lshl_add_u64 v[26:27], v[26:27], 0, v[204:205]
	global_load_dwordx4 v[84:87], v[26:27], off
	global_load_dwordx4 v[80:83], v[26:27], off offset:32
	global_load_dwordx4 v[76:79], v[26:27], off offset:64
	global_load_dwordx4 v[72:75], v[26:27], off offset:96
	global_load_dwordx4 v[68:71], v[26:27], off offset:128
	global_load_dwordx4 v[64:67], v[26:27], off offset:160
	v_and_b32_e32 v26, 0xfffff0, v130
	v_lshlrev_b32_e32 v27, 1, v130
	v_and_or_b32 v26, v27, 8, v26
	v_lshrrev_b32_e32 v26, 1, v26
	v_bfe_u32 v28, v28, 5, 1
	v_lshrrev_b32_e32 v27, 1, v130
	v_or_b32_e32 v26, v26, v28
	v_and_b32_e32 v28, 3, v130
	v_and_or_b32 v27, v27, 4, v28
	v_and_b32_e32 v28, 48, v48
	v_lshl_or_b32 v27, v27, 6, v28
	v_lshlrev_b32_e32 v28, 4, v130
	v_lshl_or_b32 v26, v26, 9, v27
	v_lshlrev_b32_e32 v27, 8, v130
	v_and_b32_e32 v28, 0xf0, v28
	s_or_b32 s12, s10, 0x80
	v_bitop3_b32 v27, v48, v27, v28 bitop3:0xde
	v_lshlrev_b32_e32 v30, 2, v52
	v_add_u32_e32 v145, 0, v26
	s_ashr_i32 s13, s12, 31
	v_lshlrev_b32_e32 v28, 8, v132
	v_or_b32_e32 v29, 0x80, v50
	v_and_b32_e32 v30, 0xf0, v30
	s_waitcnt vmcnt(0)
	v_add_u32_e32 v146, 0, v27
	v_bitop3_b32 v28, v29, v28, v30 bitop3:0xde
	v_add_u32_e32 v147, 0, v28
	v_and_b32_e32 v140, 31, v52
	v_and_b32_e32 v56, 63, v52
	v_and_b32_e32 v128, 0xffffffe0, v54
	v_readlane_b32 s76, v255, 19
	v_readlane_b32 s77, v255, 20
	v_readlane_b32 s78, v255, 21
	v_readlane_b32 s79, v255, 22
	v_readlane_b32 s80, v255, 23
	v_readlane_b32 s81, v255, 24
	v_readlane_b32 s82, v255, 25
	v_readlane_b32 s83, v255, 26
	v_readlane_b32 s84, v255, 27
	v_readlane_b32 s85, v255, 28
	v_readlane_b32 s86, v255, 29
	v_readlane_b32 s87, v255, 30
	v_readlane_b32 s88, v255, 31
	v_readlane_b32 s89, v255, 32
	v_readlane_b32 s90, v255, 33
	v_readlane_b32 s91, v255, 34
	s_mov_b32 s76, s77
	s_mov_b32 s78, s77
	s_mov_b32 s79, s77
	s_mov_b32 s80, s77
	s_mov_b32 s81, s77
	s_mov_b32 s82, s77
	s_mov_b32 s83, s77
	s_mov_b32 s84, s77
	s_mov_b32 s85, s77
	s_mov_b32 s86, s77
	s_mov_b32 s87, s77
	s_mov_b32 s88, s77
	s_waitcnt vmcnt(0)
	ds_write_b128 v145, v[0:3]
	v_lshl_add_u64 v[0:1], v[130:131], 0, s[12:13]
	ds_write_b128 v146, v[4:7] offset:32768
	v_lshlrev_b64 v[2:3], 9, v[0:1]
	v_mad_u64_u32 v[4:5], s[28:29], v0, s70, v[24:25]
	v_lshl_add_u64 v[2:3], s[4:5], 0, v[2:3]
	v_mad_i32_i24 v5, v1, s70, v5
	ds_write_b128 v147, v[8:11] offset:32768
	ds_write_b128 v145, v[12:15] offset:16384
	ds_write_b128 v146, v[16:19] offset:49152
	ds_write_b128 v147, v[20:23] offset:49152
	v_lshl_add_u64 v[2:3], v[2:3], 0, v[48:49]
	s_mov_b32 s98, 0xffff8000
	s_mov_b32 s99, -1
	v_lshl_add_u64 v[2:3], v[2:3], 0, s[98:99]
	v_lshl_add_u64 v[0:1], v[4:5], 0, v[48:49]
	global_load_dwordx4 v[92:95], v[2:3], off
	global_load_dwordx4 v[88:91], v[0:1], off
	v_or_b32_e32 v0, s12, v132
	v_mad_i64_i32 v[0:1], s[12:13], v0, s70, v[24:25]
	v_lshl_add_u64 v[0:1], v[0:1], 0, v[50:51]
	v_lshlrev_b32_e32 v8, 8, v140
	v_and_b32_e32 v9, 0xf0, v53
	global_load_dwordx4 v[96:99], v[0:1], off offset:128
	v_bitop3_b32 v0, v204, v8, v9 bitop3:0xde
	v_add_u32_e32 v148, 0, v0
	s_waitcnt lgkmcnt(0)
	s_barrier
; template <int DQK> __device__ __forceinline__ void partialSM(f32x16& p0, f32x16& p1, float& m_reg, float& mn, float& alpha) {
;   constexpr float SCALE = (DQK == 96) ? 0.10206207261596577f : 0.125f;
;   constexpr float C = SCALE * 1.4426950408889634f;
;   float pmax = p0[0];
; #pragma unroll
;   for (int r = 1; r < 16; ++r) pmax = fmaxf(pmax, p0[r]);
; #pragma unroll
;   for (int r = 0; r < 16; ++r) pmax = fmaxf(pmax, p1[r]);
;   { auto rr = __builtin_amdgcn_permlane32_swap(__float_as_uint(pmax), __float_as_uint(pmax), false, false);
;     pmax = fmaxf(__uint_as_float(rr[0]), __uint_as_float(rr[1])); }
;   if (__builtin_expect(__all(pmax - m_reg <= THR / SCALE), 1)) { mn = m_reg; alpha = 1.f; }
;   else { mn = fmaxf(m_reg, pmax); alpha = __builtin_amdgcn_exp2f((m_reg - mn) * C); m_reg = mn; }
;   float mnC = -mn * C;
; #pragma unroll
;   for (int r = 0; r < 16; ++r) p0[r] = fmaf(p0[r], C, mnC);
; #pragma unroll
;   for (int r = 0; r < 16; ++r) p1[r] = fmaf(p1[r], C, mnC);
; #pragma unroll
;   for (int r = 0; r < 16; ++r) p0[r] = __builtin_amdgcn_exp2f(p0[r]);
; }
; template <int DQK> __device__ __forceinline__ void qkt(f32x16& p0, f32x16& p1, const char* Ks, const bf16x8* qr, int r32, int hi) {
;   p0 = f32x16{}; p1 = f32x16{};
; #pragma unroll
;   for (int d0 = 0; d0 < DQK / 16; ++d0) { int cb = (d0 * 16 + hi * 8) * 2;
;     bf16x8 b0 = *reinterpret_cast<const bf16x8*>(Ks + KSWZ(r32, cb));
;     bf16x8 b1 = *reinterpret_cast<const bf16x8*>(Ks + KSWZ(32 + r32, cb));
;     p0 = __builtin_amdgcn_mfma_f32_32x32x16_bf16(b0, qr[d0], p0, 0, 0, 0);
;     p1 = __builtin_amdgcn_mfma_f32_32x32x16_bf16(b1, qr[d0], p1, 0, 0, 0); }
; }
	ds_read_b128 v[0:3], v148 offset:32768
	ds_read_b128 v[4:7], v148 offset:40960
	s_waitcnt lgkmcnt(1)
	v_mfma_f32_32x32x16_bf16 v[32:47], v[0:3], v[84:87], 0
	v_or_b32_e32 v0, 32, v204
	v_bitop3_b32 v0, v0, v8, v9 bitop3:0xde
	v_add_u32_e32 v152, 0, v0
	v_lshlrev_b32_e32 v10, 3, v56
	v_and_b32_e32 v11, 0xc0, v53
	s_mov_b32 s89, s77
	s_mov_b32 s90, s77
	s_waitcnt lgkmcnt(0)
	v_mfma_f32_32x32x16_bf16 v[16:31], v[4:7], v[84:87], 0
	ds_read_b128 v[0:3], v152 offset:32768
	ds_read_b128 v[4:7], v152 offset:40960
	s_mov_b32 s91, s77
	v_lshl_add_u64 v[134:135], s[4:5], 0, v[48:49]
	v_lshl_add_u64 v[136:137], s[0:1], 0, v[48:49]
	s_mov_b32 s13, s77
	s_mov_b32 s11, 4
	v_lshl_add_u64 v[138:139], s[0:1], 0, v[50:51]
	s_sub_u32 s98, s0, s18
	s_sub_u32 s99, s4, s20
	v_mad_u32_u24 v230, v130, s70, v48
	v_lshl_add_u32 v231, v130, 9, v48
	v_mad_u32_u24 v232, v132, s70, v50
	v_add_u32_e32 v230, s98, v230
	v_add_u32_e32 v231, s99, v231
	v_add_u32_e32 v232, s98, v232
	s_waitcnt lgkmcnt(1)
	v_mfma_f32_32x32x16_bf16 v[32:47], v[0:3], v[80:83], v[32:47]
	v_or_b32_e32 v0, 64, v204
	v_bitop3_b32 v0, v0, v8, v9 bitop3:0xde
	v_add_u32_e32 v151, 0, v0
	v_cmp_gt_u32_e64 s[4:5], 32, v56
	v_mov_b32_e32 v142, 0
	s_waitcnt lgkmcnt(0)
	v_mfma_f32_32x32x16_bf16 v[16:31], v[4:7], v[80:83], v[16:31]
	ds_read_b128 v[0:3], v151 offset:32768
	ds_read_b128 v[4:7], v151 offset:40960
	s_waitcnt lgkmcnt(1)
	v_mfma_f32_32x32x16_bf16 v[32:47], v[0:3], v[76:79], v[32:47]
	v_or_b32_e32 v0, 0x60, v204
	v_bitop3_b32 v0, v0, v8, v9 bitop3:0xde
	v_add_u32_e32 v149, 0, v0
	ds_read_b128 v[0:3], v149 offset:32768
	s_waitcnt lgkmcnt(1)
	v_mfma_f32_32x32x16_bf16 v[16:31], v[4:7], v[76:79], v[16:31]
	v_and_b32_e32 v4, 0x3fffffc0, v52
	v_lshl_add_u32 v57, v4, 2, s26
	ds_read_b128 v[4:7], v149 offset:40960
	v_lshl_add_u32 v141, v140, 2, v57
	v_add_u32_e32 v129, v57, v204
	s_waitcnt lgkmcnt(1)
	v_mfma_f32_32x32x16_bf16 v[32:47], v[0:3], v[72:75], v[32:47]
	v_or_b32_e32 v0, 0x80, v204
	v_bitop3_b32 v0, v0, v8, v9 bitop3:0xde
	v_add_u32_e32 v150, 0, v0
	ds_read_b128 v[0:3], v150 offset:32768
	s_waitcnt lgkmcnt(1)
	v_mfma_f32_32x32x16_bf16 v[16:31], v[4:7], v[72:75], v[16:31]
	v_lshlrev_b32_e32 v5, 1, v52
	v_and_or_b32 v4, v10, 24, v11
	v_and_b32_e32 v5, 32, v5
	v_and_b32_e32 v6, 0x100, v10
	v_or3_b32 v58, v4, v5, v6
	ds_read_b128 v[4:7], v150 offset:40960
	v_add_u32_e32 v144, s25, v58
	s_waitcnt lgkmcnt(1)
	v_mfma_f32_32x32x16_bf16 v[32:47], v[0:3], v[68:71], v[32:47]
	v_or_b32_e32 v0, 0xa0, v204
	v_bitop3_b32 v0, v0, v8, v9 bitop3:0xde
	v_add_u32_e32 v153, 0, v0
	ds_read_b128 v[0:3], v153 offset:32768
	ds_read_b128 v[52:55], v153 offset:40960
	v_writelane_b32 v255, s12, 19
	s_waitcnt lgkmcnt(2)
	v_mfma_f32_32x32x16_bf16 v[16:31], v[4:7], v[68:71], v[16:31]
	v_writelane_b32 v255, s13, 20
	v_writelane_b32 v255, s14, 21
	v_writelane_b32 v255, s15, 22
	v_writelane_b32 v255, s16, 23
	v_writelane_b32 v255, s17, 24
	v_writelane_b32 v255, s18, 25
	v_writelane_b32 v255, s19, 26
	s_waitcnt lgkmcnt(1)
	v_mfma_f32_32x32x16_bf16 v[32:47], v[0:3], v[64:67], v[32:47]
	v_mov_b64_e32 v[0:1], s[76:77]
	v_mov_b64_e32 v[2:3], s[78:79]
	v_mov_b64_e32 v[4:5], s[80:81]
	v_mov_b64_e32 v[6:7], s[82:83]
	v_mov_b64_e32 v[8:9], s[84:85]
	v_mov_b64_e32 v[10:11], s[86:87]
	v_mov_b64_e32 v[12:13], s[88:89]
	s_waitcnt lgkmcnt(0)
	v_mfma_f32_32x32x16_bf16 v[16:31], v[52:55], v[64:67], v[16:31]
	s_nop 2
	v_max_f32_e32 v52, v33, v33
	v_max_f32_e32 v53, v32, v32
	v_max_f32_e32 v52, v53, v52
	v_max3_f32 v52, v52, v34, v35
	v_max3_f32 v52, v52, v36, v37
	v_max3_f32 v52, v52, v38, v39
	v_max3_f32 v52, v52, v40, v41
	v_max3_f32 v52, v52, v42, v43
	v_max3_f32 v52, v52, v44, v45
	v_max3_f32 v52, v52, v46, v47
	v_max3_f32 v52, v52, v16, v17
	v_max3_f32 v52, v52, v18, v19
	v_max3_f32 v52, v52, v20, v21
	v_max3_f32 v52, v52, v22, v23
	v_max3_f32 v52, v52, v24, v25
	v_max3_f32 v52, v52, v26, v27
	v_max3_f32 v52, v52, v28, v29
	v_max3_f32 v52, v52, v30, v31
	v_mov_b32_e32 v53, v52
	s_nop 1
	v_permlane32_swap_b32_e32 v52, v53
	v_max_f32_e32 v53, v53, v53
	v_max_f32_e32 v52, v52, v52
	v_max_f32_e32 v52, v52, v53
	v_mov_b64_e32 v[14:15], s[90:91]
	s_mov_b32 s80, 0x429cc470
	v_add_f32_e32 v53, 0x7149f2ca, v52
	v_cmp_ge_f32_e32 vcc, s80, v53
	s_cmp_eq_u64 vcc, exec
	v_max_f32_e32 v49, 0xf149f2ca, v52
	s_cselect_b64 vcc, -1, 0
	v_cndmask_b32_e32 v116, v49, v248, vcc
	v_mul_f32_e32 v48, 0xbe16c740, v116
	v_fmamk_f32 v32, v32, 0x3e16c740, v48
	v_exp_f32_e32 v126, v32
	v_fmamk_f32 v32, v33, 0x3e16c740, v48
	v_exp_f32_e32 v160, v32
	v_fmamk_f32 v32, v34, 0x3e16c740, v48
	v_exp_f32_e32 v127, v32
	v_fmamk_f32 v32, v35, 0x3e16c740, v48
	v_exp_f32_e32 v161, v32
	v_fmamk_f32 v32, v36, 0x3e16c740, v48
	v_exp_f32_e32 v158, v32
	v_fmamk_f32 v32, v37, 0x3e16c740, v48
	v_exp_f32_e32 v162, v32
	v_fmamk_f32 v32, v38, 0x3e16c740, v48
	v_exp_f32_e32 v159, v32
	v_fmamk_f32 v32, v39, 0x3e16c740, v48
	v_writelane_b32 v255, s20, 27
	v_exp_f32_e32 v163, v32
	v_fmamk_f32 v32, v40, 0x3e16c740, v48
	v_writelane_b32 v255, s21, 28
	v_exp_f32_e32 v118, v32
	v_fmamk_f32 v32, v41, 0x3e16c740, v48
	v_writelane_b32 v255, s22, 29
	v_exp_f32_e32 v121, v32
	v_fmamk_f32 v32, v42, 0x3e16c740, v48
	v_sub_f32_e32 v33, 0xf149f2ca, v49
	v_writelane_b32 v255, s23, 30
	v_exp_f32_e32 v119, v32
	v_fmamk_f32 v32, v43, 0x3e16c740, v48
	v_mul_f32_e32 v33, 0x3e16c740, v33
	v_writelane_b32 v255, s24, 31
	v_exp_f32_e32 v122, v32
	v_fmamk_f32 v32, v44, 0x3e16c740, v48
	v_exp_f32_e32 v33, v33
	v_writelane_b32 v255, s25, 32
	v_exp_f32_e32 v120, v32
	v_fmamk_f32 v32, v45, 0x3e16c740, v48
	v_writelane_b32 v255, s26, 33
	v_exp_f32_e32 v123, v32
	v_fmamk_f32 v32, v46, 0x3e16c740, v48
	v_writelane_b32 v255, s27, 34
	v_exp_f32_e32 v124, v32
	v_fmamk_f32 v32, v47, 0x3e16c740, v48
	v_pk_fma_f32 v[100:101], v[30:31], s[40:41], v[48:49] op_sel_hi:[1,0,0]
	v_pk_fma_f32 v[106:107], v[28:29], s[40:41], v[48:49] op_sel_hi:[1,0,0]
	v_pk_fma_f32 v[110:111], v[26:27], s[40:41], v[48:49] op_sel_hi:[1,0,0]
	v_pk_fma_f32 v[102:103], v[24:25], s[40:41], v[48:49] op_sel_hi:[1,0,0]
	v_pk_fma_f32 v[104:105], v[22:23], s[40:41], v[48:49] op_sel_hi:[1,0,0]
	v_pk_fma_f32 v[108:109], v[20:21], s[40:41], v[48:49] op_sel_hi:[1,0,0]
	v_pk_fma_f32 v[112:113], v[18:19], s[40:41], v[48:49] op_sel_hi:[1,0,0]
	v_pk_fma_f32 v[114:115], v[16:17], s[40:41], v[48:49] op_sel_hi:[1,0,0]
	s_addk_i32 s25, 0x4000
	v_mov_b64_e32 v[30:31], v[14:15]
	s_mov_b64 s[84:85], 0x90000
	s_movk_i32 s83, 0x6000
	s_movk_i32 s82, 0x100
	v_readlane_b32 s89, v255, 47
	v_readlane_b32 s76, v255, 37
	s_movk_i32 s90, 0x1fff
	s_mov_b32 s88, 0x42800000
	s_movk_i32 s87, 0x7000
	s_movk_i32 s86, 0x1200
	s_movk_i32 s81, 0x5000
	s_movk_i32 s78, 0x4000
	v_exp_f32_e32 v125, v32
	v_cndmask_b32_e64 v154, v33, 1.0, vcc
	v_add_u32_e32 v143, s25, v58
	v_mov_b64_e32 v[28:29], v[12:13]
	v_mov_b64_e32 v[26:27], v[10:11]
	v_mov_b64_e32 v[24:25], v[8:9]
	v_mov_b64_e32 v[22:23], v[6:7]
	v_mov_b64_e32 v[20:21], v[4:5]
	v_mov_b64_e32 v[18:19], v[2:3]
	v_mov_b64_e32 v[16:17], v[0:1]
	s_barrier
	.p2align 8
; #define SBAR() __builtin_amdgcn_sched_barrier(0)
; #define SLOAD(i, j) do { const long kr_ = KROW(j); sr_[i].vs0 = ld8(Vp + (kr_ + sr) * ldv + sc); sr_[i].ks0 = ld8(Kp + (kr_ + sr) * ldk + sc); \
;     if (DQK == 96) sr_[i].ks1 = ld8(Kp + (kr_ + sr2) * ldk + sc2); } while (0)
; __device__ __forceinline__ void finishSM(f32x16& p0, f32x16& p1, float alpha, float& l_reg, bf16x8& pa0, bf16x8& pa1, bf16x8& pa2, bf16x8& pa3) {
; #pragma unroll
;   for (int r = 0; r < 16; ++r) p1[r] = __builtin_amdgcn_exp2f(p1[r]);
;   float ps = 0;
; #pragma unroll
;   for (int r = 0; r < 16; ++r) ps += p0[r];
; #pragma unroll
;   for (int r = 0; r < 16; ++r) ps += p1[r];
;   { auto rr = __builtin_amdgcn_permlane32_swap(__float_as_uint(ps), __float_as_uint(ps), false, false);
;     ps = __uint_as_float(rr[0]) + __uint_as_float(rr[1]); }
;   l_reg = l_reg * alpha + ps;
;     ...
;   PK4(p0, 0, pa0); PK4(p0, 8, pa1); PK4(p1, 0, pa2); PK4(p1, 8, pa3);
;     ...
; }
; template <int DQK> __device__ __forceinline__ void qkt(f32x16& p0, f32x16& p1, const char* Ks, const bf16x8* qr, int r32, int hi) {
;   p0 = f32x16{}; p1 = f32x16{};
; #pragma unroll
;   for (int d0 = 0; d0 < DQK / 16; ++d0) { int cb = (d0 * 16 + hi * 8) * 2;
;     bf16x8 b0 = *reinterpret_cast<const bf16x8*>(Ks + KSWZ(r32, cb));
;     bf16x8 b1 = *reinterpret_cast<const bf16x8*>(Ks + KSWZ(32 + r32, cb));
;     p0 = __builtin_amdgcn_mfma_f32_32x32x16_bf16(b0, qr[d0], p0, 0, 0, 0);
;     p1 = __builtin_amdgcn_mfma_f32_32x32x16_bf16(b1, qr[d0], p1, 0, 0, 0); }
; }
; template <int DQK, int MODE, int ldq, int ldk, int ldv> ...
;     ...
;   for (int j = 1; j + 1 < NT; j += 2) {
;     SBAR(); qkt<DQK>(pB0, pB1, K_lds + SHM_K, qr, r32, hi);
;     finishSM(pA0, pA1, alA, l_reg, pa0, pa1, pa2, pa3); SBAR();
;     SLOAD(SO, j + 2); SBAR();
.LBB0_300:
	s_add_i32 s25, s11, -3
	s_cmp_lg_u32 s32, 0
	s_cbranch_scc1 .Lmy_h1B
	ds_read_b128 v[32:35], v148 offset:49152
	ds_read_b128 v[36:39], v148 offset:57344
	ds_read_b128 v[164:167], v152 offset:49152
	ds_read_b128 v[168:171], v152 offset:57344
	ds_read_b128 v[184:187], v151 offset:49152
	ds_read_b128 v[188:191], v151 offset:57344
	s_waitcnt lgkmcnt(5)
	v_mfma_f32_32x32x16_bf16 v[48:63], v[32:35], v[84:87], 0
	s_waitcnt lgkmcnt(4)
	v_mfma_f32_32x32x16_bf16 v[32:47], v[36:39], v[84:87], 0
	s_waitcnt lgkmcnt(3)
	v_mfma_f32_32x32x16_bf16 v[48:63], v[164:167], v[80:83], v[48:63]
	s_waitcnt lgkmcnt(2)
	v_mfma_f32_32x32x16_bf16 v[32:47], v[168:171], v[80:83], v[32:47]
	ds_read_b128 v[164:167], v149 offset:49152
	ds_read_b128 v[168:171], v149 offset:57344
	s_waitcnt lgkmcnt(3)
	v_mfma_f32_32x32x16_bf16 v[48:63], v[184:187], v[76:79], v[48:63]
	s_waitcnt lgkmcnt(2)
	v_mfma_f32_32x32x16_bf16 v[32:47], v[188:191], v[76:79], v[32:47]
	ds_read_b128 v[184:187], v150 offset:49152
	ds_read_b128 v[188:191], v150 offset:57344
	s_waitcnt lgkmcnt(3)
	v_mfma_f32_32x32x16_bf16 v[48:63], v[164:167], v[72:75], v[48:63]
	s_waitcnt lgkmcnt(2)
	v_mfma_f32_32x32x16_bf16 v[32:47], v[168:171], v[72:75], v[32:47]
	ds_read_b128 v[164:167], v153 offset:49152
	ds_read_b128 v[168:171], v153 offset:57344
	s_waitcnt lgkmcnt(3)
	v_mfma_f32_32x32x16_bf16 v[48:63], v[184:187], v[68:71], v[48:63]
	s_waitcnt lgkmcnt(2)
	v_mfma_f32_32x32x16_bf16 v[32:47], v[188:191], v[68:71], v[32:47]
	s_waitcnt vmcnt(0)
	ds_write_b128 v146, v[88:91] offset:32768
	ds_write_b128 v147, v[96:99] offset:32768
	ds_write_b128 v145, v[92:95] offset:16384
	s_waitcnt lgkmcnt(4)
	v_mfma_f32_32x32x16_bf16 v[48:63], v[164:167], v[64:67], v[48:63]
	s_waitcnt lgkmcnt(3)
	v_mfma_f32_32x32x16_bf16 v[32:47], v[168:171], v[64:67], v[32:47]
	ds_read_b64_tr_b16 v[192:193], v144 offset:0
	ds_read_b64_tr_b16 v[194:195], v144 offset:0x800
	ds_read_b64_tr_b16 v[196:197], v144 offset:0x1000
	ds_read_b64_tr_b16 v[198:199], v144 offset:0x1800
	ds_read_b64_tr_b16 v[200:201], v144 offset:0x2000
	ds_read_b64_tr_b16 v[202:203], v144 offset:0x2800
	ds_read_b64_tr_b16 v[210:211], v144 offset:0x3000
	ds_read_b64_tr_b16 v[212:213], v144 offset:0x3800
	v_exp_f32_e32 v117, v114
	v_exp_f32_e32 v157, v115
	v_exp_f32_e32 v108, v108
	v_exp_f32_e32 v109, v109
	v_exp_f32_e32 v104, v104
	v_exp_f32_e32 v105, v105
	v_exp_f32_e32 v102, v102
	v_exp_f32_e32 v103, v103
	v_exp_f32_e32 v110, v110
	v_exp_f32_e32 v111, v111
	v_exp_f32_e32 v106, v106
	v_exp_f32_e32 v107, v107
	v_exp_f32_e32 v100, v100
	v_exp_f32_e32 v101, v101
	v_exp_f32_e32 v164, v112
	v_add_f32_e32 v112, 0, v126
	v_add_f32_e32 v112, v160, v112
	v_add_f32_e32 v112, v127, v112
	v_add_f32_e32 v112, v161, v112
	v_add_f32_e32 v112, v158, v112
	v_add_f32_e32 v112, v162, v112
	v_add_f32_e32 v112, v159, v112
	v_add_f32_e32 v112, v163, v112
	v_add_f32_e32 v112, v118, v112
	v_add_f32_e32 v112, v121, v112
	v_add_f32_e32 v112, v119, v112
	v_add_f32_e32 v112, v122, v112
	v_add_f32_e32 v112, v120, v112
	v_add_f32_e32 v112, v123, v112
	v_add_f32_e32 v112, v124, v112
	v_exp_f32_e32 v165, v113
	v_add_f32_e32 v112, v125, v112
	v_add_f32_e32 v112, v117, v112
	v_add_f32_e32 v112, v157, v112
	v_add_f32_e32 v112, v164, v112
	v_add_f32_e32 v112, v165, v112
	v_add_f32_e32 v112, v108, v112
	v_add_f32_e32 v112, v109, v112
	v_add_f32_e32 v112, v104, v112
	v_add_f32_e32 v112, v105, v112
	v_add_f32_e32 v112, v102, v112
	v_add_f32_e32 v112, v103, v112
	v_add_f32_e32 v112, v110, v112
	v_add_f32_e32 v112, v111, v112
	v_add_f32_e32 v112, v106, v112
	v_add_f32_e32 v112, v107, v112
	v_add_f32_e32 v112, v100, v112
	v_add_f32_e32 v155, v101, v112
	v_mov_b32_e32 v156, v155
	v_cvt_pk_bf16_f32 v214, v126, v160
	v_cvt_pk_bf16_f32 v215, v127, v161
	v_cvt_pk_bf16_f32 v216, v158, v162
	s_nop 1
	v_permlane32_swap_b32_e32 v155, v156
	v_cvt_pk_bf16_f32 v217, v159, v163
	v_permlane32_swap_b32_e32 v214, v216
	v_cvt_pk_bf16_f32 v218, v118, v121
	v_cvt_pk_bf16_f32 v219, v119, v122
	v_cvt_pk_bf16_f32 v220, v120, v123
	v_cvt_pk_bf16_f32 v221, v124, v125
	v_cvt_pk_bf16_f32 v222, v117, v157
	v_cvt_pk_bf16_f32 v223, v164, v165
	v_cvt_pk_bf16_f32 v224, v108, v109
	v_cvt_pk_bf16_f32 v225, v104, v105
	v_cvt_pk_bf16_f32 v226, v102, v103
	v_cvt_pk_bf16_f32 v227, v110, v111
	v_cvt_pk_bf16_f32 v228, v106, v107
	v_cvt_pk_bf16_f32 v229, v100, v101
	v_permlane32_swap_b32_e32 v215, v217
	v_permlane32_swap_b32_e32 v218, v220
	v_permlane32_swap_b32_e32 v219, v221
	v_permlane32_swap_b32_e32 v222, v224
	v_permlane32_swap_b32_e32 v223, v225
	v_permlane32_swap_b32_e32 v226, v228
	v_permlane32_swap_b32_e32 v227, v229
	s_cmpk_lt_u32 s25, 0x7e
	s_cselect_b32 s0, 0, 0xffffff80
	s_cselect_b32 s1, s10, s24
	s_add_i32 s0, s0, s11
	s_lshl_b32 s0, s0, 6
	s_add_i32 s0, s0, s1
	s_sub_i32 s0, s0, 64
	s_ashr_i32 s1, s0, 31
	s_cmpk_lt_u32 s25, 0x7f
	s_cselect_b32 s98, 0, 0xffffff80
	s_cselect_b32 s99, s10, s24
	s_add_i32 s98, s98, s11
	s_lshl_b32 s98, s98, 6
	s_add_i32 s98, s98, s99
	s_addk_i32 s98, 0xff80
	s_ashr_i32 s99, s98, 31
	s_mul_i32 s1, s0, 0x300
	s_add_u32 s12, s18, s1
	s_addc_u32 s13, s19, 0
	s_lshl_b32 s98, s98, 9
	s_add_u32 s98, s20, s98
	s_addc_u32 s99, s21, 0
	global_load_dwordx4 v[100:103], v230, s[12:13]
	global_load_dwordx4 v[108:111], v231, s[98:99]
	global_load_dwordx4 v[104:107], v232, s[12:13] offset:128
	s_waitcnt lgkmcnt(0)
; #define SBAR() __builtin_amdgcn_sched_barrier(0)
; template <int DQK> __device__ __forceinline__ void partialSM(f32x16& p0, f32x16& p1, float& m_reg, float& mn, float& alpha) {
;   constexpr float SCALE = (DQK == 96) ? 0.10206207261596577f : 0.125f;
;   constexpr float C = SCALE * 1.4426950408889634f;
;   float pmax = p0[0];
; #pragma unroll
;   for (int r = 1; r < 16; ++r) pmax = fmaxf(pmax, p0[r]);
; #pragma unroll
;   for (int r = 0; r < 16; ++r) pmax = fmaxf(pmax, p1[r]);
;   { auto rr = __builtin_amdgcn_permlane32_swap(__float_as_uint(pmax), __float_as_uint(pmax), false, false);
;     pmax = fmaxf(__uint_as_float(rr[0]), __uint_as_float(rr[1])); }
;   if (__builtin_expect(__all(pmax - m_reg <= THR / SCALE), 1)) { mn = m_reg; alpha = 1.f; }
;   else { mn = fmaxf(m_reg, pmax); alpha = __builtin_amdgcn_exp2f((m_reg - mn) * C); m_reg = mn; }
;   float mnC = -mn * C;
; #pragma unroll
;   for (int r = 0; r < 16; ++r) p0[r] = fmaf(p0[r], C, mnC);
; #pragma unroll
;   for (int r = 0; r < 16; ++r) p1[r] = fmaf(p1[r], C, mnC);
; #pragma unroll
;   for (int r = 0; r < 16; ++r) p0[r] = __builtin_amdgcn_exp2f(p0[r]);
; }
; template <int D0> __device__ __forceinline__ void pv_one(f32x16& od, int vb, bf16x8 pa0, bf16x8 pa1, bf16x8 pa2, bf16x8 pa3) {
;   const s16x4 l0 = tr_read<v_rd_off(D0, 0, 0)>(vb), h0 = tr_read<v_rd_off(D0, 0, 1)>(vb), l1 = tr_read<v_rd_off(D0, 1, 0)>(vb), h1 = tr_read<v_rd_off(D0, 1, 1)>(vb);
;   const s16x4 l2 = tr_read<v_rd_off(D0, 2, 0)>(vb), h2 = tr_read<v_rd_off(D0, 2, 1)>(vb), l3 = tr_read<v_rd_off(D0, 3, 0)>(vb), h3 = tr_read<v_rd_off(D0, 3, 1)>(vb);
;   asm volatile("s_waitcnt lgkmcnt(0)" ::: "memory"); SBAR();
;   od = __builtin_amdgcn_mfma_f32_32x32x16_bf16(pa0, PKLH(l0, h0), od, 0, 0, 0);
;   od = __builtin_amdgcn_mfma_f32_32x32x16_bf16(pa1, PKLH(l1, h1), od, 0, 0, 0);
;   od = __builtin_amdgcn_mfma_f32_32x32x16_bf16(pa2, PKLH(l2, h2), od, 0, 0, 0);
;   od = __builtin_amdgcn_mfma_f32_32x32x16_bf16(pa3, PKLH(l3, h3), od, 0, 0, 0);
; }
; __device__ __forceinline__ void pv_d0(f32x16* o, int vb, bf16x8 pa0, bf16x8 pa1, bf16x8 pa2, bf16x8 pa3) {
;   pv_one<0>(o[0], vb, pa0, pa1, pa2, pa3); pv_one<1>(o[1], vb, pa0, pa1, pa2, pa3);
; }
	s_nop 0
	v_mfma_f32_32x32x16_bf16 v[0:15], v[214:217], v[192:195], v[0:15]
	ds_read_b64_tr_b16 v[192:193], v144 offset:0x200
	ds_read_b64_tr_b16 v[194:195], v144 offset:0xa00
	v_max_f32_e32 v112, v48, v49
	v_max3_f32 v112, v112, v50, v51
	v_max3_f32 v112, v112, v52, v53
	v_max3_f32 v112, v112, v54, v55
	v_max3_f32 v112, v112, v56, v57
	v_max3_f32 v112, v112, v58, v59
	v_max3_f32 v112, v112, v60, v61
	v_max3_f32 v112, v112, v62, v63
	v_mfma_f32_32x32x16_bf16 v[0:15], v[218:221], v[196:199], v[0:15]
	ds_read_b64_tr_b16 v[196:197], v144 offset:0x1200
	ds_read_b64_tr_b16 v[198:199], v144 offset:0x1a00
	v_max3_f32 v112, v112, v32, v33
	v_max3_f32 v112, v112, v34, v35
	v_max3_f32 v112, v112, v36, v37
	v_max3_f32 v112, v112, v38, v39
	v_max3_f32 v112, v112, v40, v41
	v_max3_f32 v112, v112, v42, v43
	v_max3_f32 v112, v112, v44, v45
	v_max3_f32 v112, v112, v46, v47
	v_mfma_f32_32x32x16_bf16 v[0:15], v[222:225], v[200:203], v[0:15]
	ds_read_b64_tr_b16 v[200:201], v144 offset:0x2200
	ds_read_b64_tr_b16 v[202:203], v144 offset:0x2a00
	v_mov_b32_e32 v113, v112
	s_nop 1
	v_permlane32_swap_b32_e32 v112, v113
	v_max_f32_e32 v112, v112, v113
	v_sub_f32_e32 v113, v112, v116
	v_cmp_ge_f32_e32 vcc, s80, v113
	v_max_f32_e32 v112, v116, v112
	v_sub_f32_e32 v113, v116, v112
	v_mfma_f32_32x32x16_bf16 v[0:15], v[226:229], v[210:213], v[0:15]
	ds_read_b64_tr_b16 v[210:211], v144 offset:0x3200
	ds_read_b64_tr_b16 v[212:213], v144 offset:0x3a00
	v_mul_f32_e32 v113, 0x3e16c740, v113
	v_exp_f32_e32 v113, v113
	s_cmp_eq_u64 vcc, exec
	s_cselect_b64 s[0:1], -1, 0
	v_cndmask_b32_e64 v157, v113, 1.0, s[0:1]
	v_cmp_gt_f32_e32 vcc, 1.0, v157
	s_waitcnt lgkmcnt(0)
	v_mfma_f32_32x32x16_bf16 v[16:31], v[214:217], v[192:195], v[16:31]
	v_cndmask_b32_e64 v158, v112, v116, s[0:1]
	v_mul_f32_e32 v159, 0xbe16c740, v158
	v_fmamk_f32 v48, v48, 0x3e16c740, v159
	v_fmamk_f32 v49, v49, 0x3e16c740, v159
	v_fmamk_f32 v50, v50, 0x3e16c740, v159
	v_fmamk_f32 v51, v51, 0x3e16c740, v159
	v_fmamk_f32 v52, v52, 0x3e16c740, v159
	v_fmamk_f32 v53, v53, 0x3e16c740, v159
	v_fmamk_f32 v54, v54, 0x3e16c740, v159
	v_fmamk_f32 v55, v55, 0x3e16c740, v159
	v_fmamk_f32 v56, v56, 0x3e16c740, v159
	v_fmamk_f32 v57, v57, 0x3e16c740, v159
	v_fmamk_f32 v58, v58, 0x3e16c740, v159
	v_mfma_f32_32x32x16_bf16 v[16:31], v[218:221], v[196:199], v[16:31]
	v_fmamk_f32 v59, v59, 0x3e16c740, v159
	v_fmamk_f32 v60, v60, 0x3e16c740, v159
	v_fmamk_f32 v61, v61, 0x3e16c740, v159
	v_fmamk_f32 v62, v62, 0x3e16c740, v159
	v_fmamk_f32 v63, v63, 0x3e16c740, v159
	v_exp_f32_e32 v112, v48
	v_exp_f32_e32 v127, v49
	v_exp_f32_e32 v113, v50
	v_exp_f32_e32 v126, v51
	v_exp_f32_e32 v114, v52
	v_exp_f32_e32 v125, v53
	v_exp_f32_e32 v115, v54
	v_exp_f32_e32 v124, v55
	v_mfma_f32_32x32x16_bf16 v[16:31], v[222:225], v[200:203], v[16:31]
	v_exp_f32_e32 v116, v56
	v_exp_f32_e32 v123, v57
	v_exp_f32_e32 v117, v58
	v_exp_f32_e32 v122, v59
	v_exp_f32_e32 v118, v60
	v_exp_f32_e32 v121, v61
	v_exp_f32_e32 v119, v62
	v_exp_f32_e32 v120, v63
	v_fmamk_f32 v164, v42, 0x3e16c740, v159
	v_fmamk_f32 v165, v43, 0x3e16c740, v159
	v_fmamk_f32 v167, v32, 0x3e16c740, v159
	v_fmamk_f32 v168, v33, 0x3e16c740, v159
	v_fmamk_f32 v169, v34, 0x3e16c740, v159
	v_mfma_f32_32x32x16_bf16 v[16:31], v[226:229], v[210:213], v[16:31]
	v_fmamk_f32 v170, v35, 0x3e16c740, v159
	v_fmamk_f32 v171, v36, 0x3e16c740, v159
	v_fmamk_f32 v172, v37, 0x3e16c740, v159
	v_fmamk_f32 v160, v38, 0x3e16c740, v159
	v_fmamk_f32 v161, v39, 0x3e16c740, v159
	v_fmamk_f32 v162, v40, 0x3e16c740, v159
	v_fmamk_f32 v163, v41, 0x3e16c740, v159
	v_fmamk_f32 v166, v44, 0x3e16c740, v159
	v_fmamk_f32 v173, v45, 0x3e16c740, v159
	v_fmamk_f32 v174, v46, 0x3e16c740, v159
	v_fmac_f32_e32 v159, 0x3e16c740, v47
	s_cbranch_vccz .LBB0_304
	s_and_saveexec_b64 s[12:13], s[4:5]
	ds_write_b32 v141, v157 offset:128
	s_or_b64 exec, exec, s[12:13]
	s_waitcnt lgkmcnt(0)
	ds_read_b128 v[192:195], v129 offset:224
	ds_read_b128 v[196:199], v129 offset:192
	ds_read_b128 v[200:203], v129 offset:160
	ds_read_b128 v[210:213], v129 offset:128
	s_waitcnt lgkmcnt(3)
	v_pk_mul_f32 v[14:15], v[14:15], v[194:195]
	s_waitcnt lgkmcnt(2)
	v_pk_mul_f32 v[10:11], v[10:11], v[198:199]
	s_waitcnt lgkmcnt(1)
	v_pk_mul_f32 v[6:7], v[6:7], v[202:203]
	s_waitcnt lgkmcnt(0)
	v_pk_mul_f32 v[2:3], v[2:3], v[212:213]
	v_pk_mul_f32 v[12:13], v[12:13], v[192:193]
	v_pk_mul_f32 v[8:9], v[8:9], v[196:197]
	v_pk_mul_f32 v[4:5], v[4:5], v[200:201]
	v_pk_mul_f32 v[0:1], v[0:1], v[210:211]
	v_pk_mul_f32 v[30:31], v[30:31], v[194:195]
	v_pk_mul_f32 v[26:27], v[26:27], v[198:199]
	v_pk_mul_f32 v[22:23], v[22:23], v[202:203]
	v_pk_mul_f32 v[18:19], v[18:19], v[212:213]
	v_pk_mul_f32 v[28:29], v[28:29], v[192:193]
	v_pk_mul_f32 v[24:25], v[24:25], v[196:197]
	v_pk_mul_f32 v[20:21], v[20:21], v[200:201]
	v_pk_mul_f32 v[16:17], v[16:17], v[210:211]
; #define SBAR() __builtin_amdgcn_sched_barrier(0)
; #define SLOAD(i, j) do { const long kr_ = KROW(j); sr_[i].vs0 = ld8(Vp + (kr_ + sr) * ldv + sc); sr_[i].ks0 = ld8(Kp + (kr_ + sr) * ldk + sc); \
;     if (DQK == 96) sr_[i].ks1 = ld8(Kp + (kr_ + sr2) * ldk + sc2); } while (0)
; #define SWRITE(b, i) do { *(bf16x8*)(V_lds + (b) * SHM_V + vst0) = sr_[i].vs0; *(bf16x8*)(K_lds + (b) * SHM_K + kst0) = sr_[i].ks0; \
;     if (DQK == 96) *(bf16x8*)(K_lds + (b) * SHM_K + kst1) = sr_[i].ks1; } while (0)
; #define RESC(a) do { if (__any((a) < 1.f)) { if (hi == 0) al_l[r32] = (a); asm volatile("s_waitcnt lgkmcnt(0)" ::: "memory"); \
;     _Pragma("unroll") for (int d = 0; d < 2; ++d) _Pragma("unroll") for (int r = 0; r < 16; ++r) o[d][r] *= al_l[crow(r, hi)]; } } while (0)
; __device__ __forceinline__ void finishSM(f32x16& p0, f32x16& p1, float alpha, float& l_reg, bf16x8& pa0, bf16x8& pa1, bf16x8& pa2, bf16x8& pa3) {
; #pragma unroll
;   for (int r = 0; r < 16; ++r) p1[r] = __builtin_amdgcn_exp2f(p1[r]);
;   float ps = 0;
; #pragma unroll
;   for (int r = 0; r < 16; ++r) ps += p0[r];
; #pragma unroll
;   for (int r = 0; r < 16; ++r) ps += p1[r];
;   { auto rr = __builtin_amdgcn_permlane32_swap(__float_as_uint(ps), __float_as_uint(ps), false, false);
;     ps = __uint_as_float(rr[0]) + __uint_as_float(rr[1]); }
;   l_reg = l_reg * alpha + ps;
;     ...
;   PK4(p0, 0, pa0); PK4(p0, 8, pa1); PK4(p1, 0, pa2); PK4(p1, 8, pa3);
;     ...
; }
; template <int DQK> __device__ __forceinline__ void qkt(f32x16& p0, f32x16& p1, const char* Ks, const bf16x8* qr, int r32, int hi) {
;   p0 = f32x16{}; p1 = f32x16{};
; #pragma unroll
;   for (int d0 = 0; d0 < DQK / 16; ++d0) { int cb = (d0 * 16 + hi * 8) * 2;
;     bf16x8 b0 = *reinterpret_cast<const bf16x8*>(Ks + KSWZ(r32, cb));
;     bf16x8 b1 = *reinterpret_cast<const bf16x8*>(Ks + KSWZ(32 + r32, cb));
;     p0 = __builtin_amdgcn_mfma_f32_32x32x16_bf16(b0, qr[d0], p0, 0, 0, 0);
;     p1 = __builtin_amdgcn_mfma_f32_32x32x16_bf16(b1, qr[d0], p1, 0, 0, 0); }
; }
; template <int DQK, int MODE, int ldq, int ldk, int ldv> ...
;     ...
;     __syncthreads(); SWRITE(0, SE);
;     RESC(alB); __syncthreads();
;     SBAR(); qkt<DQK>(pA0, pA1, K_lds, qr, r32, hi);
;     finishSM(pB0, pB1, alB, l_reg, pa0, pa1, pa2, pa3); SBAR();
;     if (j + 3 < NT) SLOAD(SE, j + 3); SBAR();
.LBB0_304:
	s_waitcnt lgkmcnt(0)
	s_barrier
	ds_read_b128 v[32:35], v148 offset:32768
	ds_read_b128 v[36:39], v148 offset:40960
	ds_read_b128 v[176:179], v152 offset:32768
	ds_read_b128 v[180:183], v152 offset:40960
	ds_read_b128 v[184:187], v151 offset:32768
	ds_read_b128 v[188:191], v151 offset:40960
	s_waitcnt lgkmcnt(5)
	v_mfma_f32_32x32x16_bf16 v[48:63], v[32:35], v[84:87], 0
	s_waitcnt lgkmcnt(4)
	v_mfma_f32_32x32x16_bf16 v[32:47], v[36:39], v[84:87], 0
	s_waitcnt lgkmcnt(3)
	v_mfma_f32_32x32x16_bf16 v[48:63], v[176:179], v[80:83], v[48:63]
	s_waitcnt lgkmcnt(2)
	v_mfma_f32_32x32x16_bf16 v[32:47], v[180:183], v[80:83], v[32:47]
	ds_read_b128 v[176:179], v149 offset:32768
	ds_read_b128 v[180:183], v149 offset:40960
	s_waitcnt lgkmcnt(3)
	v_mfma_f32_32x32x16_bf16 v[48:63], v[184:187], v[76:79], v[48:63]
	s_waitcnt lgkmcnt(2)
	v_mfma_f32_32x32x16_bf16 v[32:47], v[188:191], v[76:79], v[32:47]
	ds_read_b128 v[184:187], v150 offset:32768
	ds_read_b128 v[188:191], v150 offset:40960
	s_waitcnt lgkmcnt(3)
	v_mfma_f32_32x32x16_bf16 v[48:63], v[176:179], v[72:75], v[48:63]
	s_waitcnt lgkmcnt(2)
	v_mfma_f32_32x32x16_bf16 v[32:47], v[180:183], v[72:75], v[32:47]
	ds_read_b128 v[176:179], v153 offset:32768
	ds_read_b128 v[180:183], v153 offset:40960
	s_waitcnt lgkmcnt(3)
	v_mfma_f32_32x32x16_bf16 v[48:63], v[184:187], v[68:71], v[48:63]
	s_waitcnt lgkmcnt(2)
	v_mfma_f32_32x32x16_bf16 v[32:47], v[188:191], v[68:71], v[32:47]
	s_waitcnt vmcnt(0)
	ds_write_b128 v146, v[100:103] offset:49152
	ds_write_b128 v147, v[104:107] offset:49152
	ds_write_b128 v145, v[108:111]
	s_waitcnt lgkmcnt(4)
	v_mfma_f32_32x32x16_bf16 v[48:63], v[176:179], v[64:67], v[48:63]
	s_waitcnt lgkmcnt(3)
	v_mfma_f32_32x32x16_bf16 v[32:47], v[180:183], v[64:67], v[32:47]
	ds_read_b64_tr_b16 v[192:193], v143 offset:0
	ds_read_b64_tr_b16 v[194:195], v143 offset:0x800
	ds_read_b64_tr_b16 v[196:197], v143 offset:0x1000
	ds_read_b64_tr_b16 v[198:199], v143 offset:0x1800
	ds_read_b64_tr_b16 v[200:201], v143 offset:0x2000
	ds_read_b64_tr_b16 v[202:203], v143 offset:0x2800
	ds_read_b64_tr_b16 v[210:211], v143 offset:0x3000
	ds_read_b64_tr_b16 v[212:213], v143 offset:0x3800
	v_exp_f32_e32 v175, v164
	v_add_f32_e32 v164, 0, v112
	v_add_f32_e32 v164, v127, v164
	v_add_f32_e32 v164, v113, v164
	v_add_f32_e32 v164, v126, v164
	v_add_f32_e32 v164, v114, v164
	v_add_f32_e32 v164, v125, v164
	v_add_f32_e32 v164, v115, v164
	v_add_f32_e32 v164, v124, v164
	v_add_f32_e32 v164, v116, v164
	v_add_f32_e32 v164, v123, v164
	v_add_f32_e32 v164, v117, v164
	v_add_f32_e32 v164, v122, v164
	v_exp_f32_e32 v167, v167
	v_add_f32_e32 v164, v118, v164
	v_exp_f32_e32 v168, v168
	v_add_f32_e32 v164, v121, v164
	v_exp_f32_e32 v169, v169
	v_add_f32_e32 v164, v119, v164
	v_exp_f32_e32 v170, v170
	v_add_f32_e32 v164, v120, v164
	v_exp_f32_e32 v171, v171
	v_add_f32_e32 v164, v167, v164
	v_exp_f32_e32 v172, v172
	v_add_f32_e32 v164, v168, v164
	v_exp_f32_e32 v160, v160
	v_add_f32_e32 v164, v169, v164
	v_exp_f32_e32 v161, v161
	v_add_f32_e32 v164, v170, v164
	v_exp_f32_e32 v162, v162
	v_add_f32_e32 v164, v171, v164
	v_exp_f32_e32 v163, v163
	v_add_f32_e32 v164, v172, v164
	v_add_f32_e32 v164, v160, v164
	v_add_f32_e32 v164, v161, v164
	v_exp_f32_e32 v166, v166
	v_add_f32_e32 v164, v162, v164
	v_exp_f32_e32 v173, v173
	v_add_f32_e32 v164, v163, v164
	v_exp_f32_e32 v174, v174
	v_add_f32_e32 v164, v175, v164
	v_exp_f32_e32 v159, v159
	v_cvt_pk_bf16_f32 v214, v112, v127
	v_cvt_pk_bf16_f32 v215, v113, v126
	v_cvt_pk_bf16_f32 v216, v114, v125
	v_cvt_pk_bf16_f32 v217, v115, v124
	v_cvt_pk_bf16_f32 v218, v116, v123
	v_cvt_pk_bf16_f32 v219, v117, v122
	v_exp_f32_e32 v176, v165
	v_cvt_pk_bf16_f32 v220, v118, v121
	v_cvt_pk_bf16_f32 v221, v119, v120
	v_cvt_pk_bf16_f32 v222, v167, v168
	v_cvt_pk_bf16_f32 v223, v169, v170
	v_cvt_pk_bf16_f32 v224, v171, v172
	s_nop 0
	v_add_f32_e32 v164, v176, v164
	v_add_f32_e32 v164, v166, v164
	v_add_f32_e32 v164, v173, v164
	v_add_f32_e32 v164, v174, v164
	v_add_f32_e32 v164, v159, v164
	v_mov_b32_e32 v165, v164
	v_cvt_pk_bf16_f32 v225, v160, v161
	v_cvt_pk_bf16_f32 v226, v162, v163
	v_cvt_pk_bf16_f32 v227, v175, v176
	v_cvt_pk_bf16_f32 v228, v166, v173
	v_cvt_pk_bf16_f32 v229, v174, v159
	s_nop 1
	v_permlane32_swap_b32_e32 v164, v165
	v_permlane32_swap_b32_e32 v214, v216
	v_permlane32_swap_b32_e32 v215, v217
	v_permlane32_swap_b32_e32 v218, v220
	v_permlane32_swap_b32_e32 v219, v221
	v_permlane32_swap_b32_e32 v222, v224
	v_permlane32_swap_b32_e32 v223, v225
	v_permlane32_swap_b32_e32 v226, v228
	v_permlane32_swap_b32_e32 v227, v229
	s_cmpk_lt_u32 s25, 0x7e
	s_cselect_b32 s98, 0, 0xffffff80
	s_cselect_b32 s99, s10, s24
	s_add_i32 s98, s98, s11
	s_lshl_b32 s98, s98, 6
	s_add_i32 s98, s98, s99
	s_sub_i32 s98, s98, 64
	s_ashr_i32 s99, s98, 31
	s_lshl_b32 s98, s98, 9
	s_add_u32 s98, s20, s98
	s_addc_u32 s99, s21, 0
	global_load_dwordx4 v[92:95], v231, s[98:99]
	s_cmpk_gt_u32 s25, 0x80
	s_cbranch_scc1 .LBB0_306
	s_cmpk_lt_u32 s25, 0x7d
	s_cselect_b32 s0, 0, 0xffffff80
	s_cselect_b32 s1, s10, s24
	s_add_i32 s0, s0, s11
	s_lshl_b32 s0, s0, 6
	s_add_i32 s0, s0, s1
	s_ashr_i32 s1, s0, 31
	s_mul_i32 s1, s0, 0x300
	s_add_u32 s12, s18, s1
	s_addc_u32 s13, s19, 0
	global_load_dwordx4 v[88:91], v230, s[12:13]
	global_load_dwordx4 v[96:99], v232, s[12:13] offset:128

; #define SBAR() __builtin_amdgcn_sched_barrier(0)
; __device__ __forceinline__ void finishSM(f32x16& p0, f32x16& p1, float alpha, float& l_reg, bf16x8& pa0, bf16x8& pa1, bf16x8& pa2, bf16x8& pa3) {
; #pragma unroll
;   for (int r = 0; r < 16; ++r) p1[r] = __builtin_amdgcn_exp2f(p1[r]);
;   float ps = 0;
; #pragma unroll
;   for (int r = 0; r < 16; ++r) ps += p0[r];
; #pragma unroll
;   for (int r = 0; r < 16; ++r) ps += p1[r];
;   { auto rr = __builtin_amdgcn_permlane32_swap(__float_as_uint(ps), __float_as_uint(ps), false, false);
;     ps = __uint_as_float(rr[0]) + __uint_as_float(rr[1]); }
;   l_reg = l_reg * alpha + ps;
;     ...
;   PK4(p0, 0, pa0); PK4(p0, 8, pa1); PK4(p1, 0, pa2); PK4(p1, 8, pa3);
;     ...
; }
; template <int DQK> __device__ __forceinline__ void qkt(f32x16& p0, f32x16& p1, const char* Ks, const bf16x8* qr, int r32, int hi) {
;   p0 = f32x16{}; p1 = f32x16{};
; #pragma unroll
;   for (int d0 = 0; d0 < DQK / 16; ++d0) { int cb = (d0 * 16 + hi * 8) * 2;
;     bf16x8 b0 = *reinterpret_cast<const bf16x8*>(Ks + KSWZ(r32, cb));
;     bf16x8 b1 = *reinterpret_cast<const bf16x8*>(Ks + KSWZ(32 + r32, cb));
;     p0 = __builtin_amdgcn_mfma_f32_32x32x16_bf16(b0, qr[d0], p0, 0, 0, 0);
;     p1 = __builtin_amdgcn_mfma_f32_32x32x16_bf16(b1, qr[d0], p1, 0, 0, 0); }
; }
; template <int D0> __device__ __forceinline__ void pv_one(f32x16& od, int vb, bf16x8 pa0, bf16x8 pa1, bf16x8 pa2, bf16x8 pa3) {
;   const s16x4 l0 = tr_read<v_rd_off(D0, 0, 0)>(vb), h0 = tr_read<v_rd_off(D0, 0, 1)>(vb), l1 = tr_read<v_rd_off(D0, 1, 0)>(vb), h1 = tr_read<v_rd_off(D0, 1, 1)>(vb);
;   const s16x4 l2 = tr_read<v_rd_off(D0, 2, 0)>(vb), h2 = tr_read<v_rd_off(D0, 2, 1)>(vb), l3 = tr_read<v_rd_off(D0, 3, 0)>(vb), h3 = tr_read<v_rd_off(D0, 3, 1)>(vb);
;   asm volatile("s_waitcnt lgkmcnt(0)" ::: "memory"); SBAR();
;   od = __builtin_amdgcn_mfma_f32_32x32x16_bf16(pa0, PKLH(l0, h0), od, 0, 0, 0);
;   od = __builtin_amdgcn_mfma_f32_32x32x16_bf16(pa1, PKLH(l1, h1), od, 0, 0, 0);
;   od = __builtin_amdgcn_mfma_f32_32x32x16_bf16(pa2, PKLH(l2, h2), od, 0, 0, 0);
;   od = __builtin_amdgcn_mfma_f32_32x32x16_bf16(pa3, PKLH(l3, h3), od, 0, 0, 0);
; }
; __device__ __forceinline__ void pv_d0(f32x16* o, int vb, bf16x8 pa0, bf16x8 pa1, bf16x8 pa2, bf16x8 pa3) {
;   pv_one<0>(o[0], vb, pa0, pa1, pa2, pa3); pv_one<1>(o[1], vb, pa0, pa1, pa2, pa3);
; }
.Lmy_h1B:
	s_waitcnt vmcnt(0)
	ds_write_b128 v146, v[88:91] offset:32768
	ds_write_b128 v145, v[92:95] offset:16384
	v_exp_f32_e32 v117, v114
	v_exp_f32_e32 v157, v115
	v_exp_f32_e32 v108, v108
	v_exp_f32_e32 v109, v109
	v_exp_f32_e32 v104, v104
	v_exp_f32_e32 v105, v105
	v_exp_f32_e32 v102, v102
	v_exp_f32_e32 v103, v103
	v_exp_f32_e32 v110, v110
	v_exp_f32_e32 v111, v111
	v_exp_f32_e32 v106, v106
	v_exp_f32_e32 v107, v107
	v_exp_f32_e32 v100, v100
	v_exp_f32_e32 v101, v101
	v_exp_f32_e32 v164, v112
	v_add_f32_e32 v112, 0, v126
	v_add_f32_e32 v112, v160, v112
	v_add_f32_e32 v112, v127, v112
	v_add_f32_e32 v112, v161, v112
	v_add_f32_e32 v112, v158, v112
	v_add_f32_e32 v112, v162, v112
	v_add_f32_e32 v112, v159, v112
	v_add_f32_e32 v112, v163, v112
	v_add_f32_e32 v112, v118, v112
	v_add_f32_e32 v112, v121, v112
	v_add_f32_e32 v112, v119, v112
	v_add_f32_e32 v112, v122, v112
	v_add_f32_e32 v112, v120, v112
	v_add_f32_e32 v112, v123, v112
	v_add_f32_e32 v112, v124, v112
	v_exp_f32_e32 v165, v113
	v_add_f32_e32 v112, v125, v112
	v_add_f32_e32 v112, v117, v112
	v_add_f32_e32 v112, v157, v112
	v_add_f32_e32 v112, v164, v112
	v_add_f32_e32 v112, v165, v112
	v_add_f32_e32 v112, v108, v112
	v_add_f32_e32 v112, v109, v112
	v_add_f32_e32 v112, v104, v112
	v_add_f32_e32 v112, v105, v112
	v_add_f32_e32 v112, v102, v112
	v_add_f32_e32 v112, v103, v112
	v_add_f32_e32 v112, v110, v112
	v_add_f32_e32 v112, v111, v112
	v_add_f32_e32 v112, v106, v112
	v_add_f32_e32 v112, v107, v112
	v_add_f32_e32 v112, v100, v112
	v_add_f32_e32 v155, v101, v112
	v_mov_b32_e32 v156, v155
	v_cvt_pk_bf16_f32 v214, v126, v160
	v_cvt_pk_bf16_f32 v215, v127, v161
	v_cvt_pk_bf16_f32 v216, v158, v162
	s_nop 1
	v_permlane32_swap_b32_e32 v155, v156
	v_cvt_pk_bf16_f32 v217, v159, v163
	v_permlane32_swap_b32_e32 v214, v216
	v_cvt_pk_bf16_f32 v218, v118, v121
	v_cvt_pk_bf16_f32 v219, v119, v122
	v_cvt_pk_bf16_f32 v220, v120, v123
	v_cvt_pk_bf16_f32 v221, v124, v125
	v_cvt_pk_bf16_f32 v222, v117, v157
	v_cvt_pk_bf16_f32 v223, v164, v165
	v_cvt_pk_bf16_f32 v224, v108, v109
	v_cvt_pk_bf16_f32 v225, v104, v105
	v_cvt_pk_bf16_f32 v226, v102, v103
	v_cvt_pk_bf16_f32 v227, v110, v111
	v_cvt_pk_bf16_f32 v228, v106, v107
	v_cvt_pk_bf16_f32 v229, v100, v101
	v_permlane32_swap_b32_e32 v215, v217
	v_permlane32_swap_b32_e32 v218, v220
	v_permlane32_swap_b32_e32 v219, v221
	v_permlane32_swap_b32_e32 v222, v224
	v_permlane32_swap_b32_e32 v223, v225
	v_permlane32_swap_b32_e32 v226, v228
	v_permlane32_swap_b32_e32 v227, v229
	s_cmpk_lt_u32 s25, 0x7e
	s_cselect_b32 s0, 0, 0xffffff80
	s_cselect_b32 s1, s10, s24
	s_add_i32 s0, s0, s11
	s_lshl_b32 s0, s0, 6
	s_add_i32 s0, s0, s1
	s_sub_i32 s0, s0, 64
	s_ashr_i32 s1, s0, 31
	s_cmpk_lt_u32 s25, 0x7f
	s_cselect_b32 s98, 0, 0xffffff80
	s_cselect_b32 s99, s10, s24
	s_add_i32 s98, s98, s11
	s_lshl_b32 s98, s98, 6
	s_add_i32 s98, s98, s99
	s_addk_i32 s98, 0xff80
	s_ashr_i32 s99, s98, 31
	s_mul_i32 s1, s0, 0x300
	s_add_u32 s12, s18, s1
	s_addc_u32 s13, s19, 0
	s_lshl_b32 s98, s98, 9
	s_add_u32 s98, s20, s98
	s_addc_u32 s99, s21, 0
	global_load_dwordx4 v[100:103], v230, s[12:13]
	global_load_dwordx4 v[108:111], v231, s[98:99]
	ds_read_b64_tr_b16 v[192:193], v144 offset:0
	ds_read_b64_tr_b16 v[194:195], v144 offset:0x800
	ds_read_b64_tr_b16 v[196:197], v144 offset:0x1000
	ds_read_b64_tr_b16 v[198:199], v144 offset:0x1800
	ds_read_b64_tr_b16 v[200:201], v144 offset:0x2000
	ds_read_b64_tr_b16 v[202:203], v144 offset:0x2800
	ds_read_b64_tr_b16 v[210:211], v144 offset:0x3000
	ds_read_b64_tr_b16 v[212:213], v144 offset:0x3800
	s_waitcnt lgkmcnt(0)
	s_nop 0
	v_mfma_f32_32x32x16_bf16 v[0:15], v[214:217], v[192:195], v[0:15]
	ds_read_b64_tr_b16 v[192:193], v144 offset:0x200
	ds_read_b64_tr_b16 v[194:195], v144 offset:0xa00
	v_mfma_f32_32x32x16_bf16 v[0:15], v[218:221], v[196:199], v[0:15]
	ds_read_b64_tr_b16 v[196:197], v144 offset:0x1200
	ds_read_b64_tr_b16 v[198:199], v144 offset:0x1a00
	v_mfma_f32_32x32x16_bf16 v[0:15], v[222:225], v[200:203], v[0:15]
	ds_read_b64_tr_b16 v[200:201], v144 offset:0x2200
	ds_read_b64_tr_b16 v[202:203], v144 offset:0x2a00
	v_mfma_f32_32x32x16_bf16 v[0:15], v[226:229], v[210:213], v[0:15]
	ds_read_b64_tr_b16 v[210:211], v144 offset:0x3200
	ds_read_b64_tr_b16 v[212:213], v144 offset:0x3a00
	s_waitcnt lgkmcnt(0)
	v_mfma_f32_32x32x16_bf16 v[16:31], v[214:217], v[192:195], v[16:31]
	v_mfma_f32_32x32x16_bf16 v[16:31], v[218:221], v[196:199], v[16:31]
	v_mfma_f32_32x32x16_bf16 v[16:31], v[222:225], v[200:203], v[16:31]
	v_mfma_f32_32x32x16_bf16 v[16:31], v[226:229], v[210:213], v[16:31]
	ds_read_b128 v[32:35], v148 offset:49152
	ds_read_b128 v[36:39], v148 offset:57344
	ds_read_b128 v[164:167], v152 offset:49152
	ds_read_b128 v[168:171], v152 offset:57344
	ds_read_b128 v[184:187], v151 offset:49152
	ds_read_b128 v[188:191], v151 offset:57344
	s_waitcnt lgkmcnt(5)
	v_mfma_f32_32x32x16_bf16 v[48:63], v[32:35], v[84:87], 0
	s_waitcnt lgkmcnt(4)
	v_mfma_f32_32x32x16_bf16 v[32:47], v[36:39], v[84:87], 0
	s_waitcnt lgkmcnt(3)
	v_mfma_f32_32x32x16_bf16 v[48:63], v[164:167], v[80:83], v[48:63]
	s_waitcnt lgkmcnt(2)
	v_mfma_f32_32x32x16_bf16 v[32:47], v[168:171], v[80:83], v[32:47]
	ds_read_b128 v[164:167], v149 offset:49152
	ds_read_b128 v[168:171], v149 offset:57344
	s_waitcnt lgkmcnt(3)
	v_mfma_f32_32x32x16_bf16 v[48:63], v[184:187], v[76:79], v[48:63]
	s_waitcnt lgkmcnt(2)
	v_mfma_f32_32x32x16_bf16 v[32:47], v[188:191], v[76:79], v[32:47]
	ds_read_b128 v[184:187], v150 offset:49152
	ds_read_b128 v[188:191], v150 offset:57344
	s_waitcnt lgkmcnt(3)
	v_mfma_f32_32x32x16_bf16 v[48:63], v[164:167], v[72:75], v[48:63]
	s_waitcnt lgkmcnt(2)
; template <int DQK> __device__ __forceinline__ void partialSM(f32x16& p0, f32x16& p1, float& m_reg, float& mn, float& alpha) {
;   constexpr float SCALE = (DQK == 96) ? 0.10206207261596577f : 0.125f;
;   constexpr float C = SCALE * 1.4426950408889634f;
;   float pmax = p0[0];
; #pragma unroll
;   for (int r = 1; r < 16; ++r) pmax = fmaxf(pmax, p0[r]);
; #pragma unroll
;   for (int r = 0; r < 16; ++r) pmax = fmaxf(pmax, p1[r]);
;   { auto rr = __builtin_amdgcn_permlane32_swap(__float_as_uint(pmax), __float_as_uint(pmax), false, false);
;     pmax = fmaxf(__uint_as_float(rr[0]), __uint_as_float(rr[1])); }
;   if (__builtin_expect(__all(pmax - m_reg <= THR / SCALE), 1)) { mn = m_reg; alpha = 1.f; }
;   else { mn = fmaxf(m_reg, pmax); alpha = __builtin_amdgcn_exp2f((m_reg - mn) * C); m_reg = mn; }
;   float mnC = -mn * C;
; #pragma unroll
;   for (int r = 0; r < 16; ++r) p0[r] = fmaf(p0[r], C, mnC);
; #pragma unroll
;   for (int r = 0; r < 16; ++r) p1[r] = fmaf(p1[r], C, mnC);
; #pragma unroll
;   for (int r = 0; r < 16; ++r) p0[r] = __builtin_amdgcn_exp2f(p0[r]);
; }
; template <int DQK> __device__ __forceinline__ void qkt(f32x16& p0, f32x16& p1, const char* Ks, const bf16x8* qr, int r32, int hi) {
;   p0 = f32x16{}; p1 = f32x16{};
; #pragma unroll
;   for (int d0 = 0; d0 < DQK / 16; ++d0) { int cb = (d0 * 16 + hi * 8) * 2;
;     bf16x8 b0 = *reinterpret_cast<const bf16x8*>(Ks + KSWZ(r32, cb));
;     bf16x8 b1 = *reinterpret_cast<const bf16x8*>(Ks + KSWZ(32 + r32, cb));
;     p0 = __builtin_amdgcn_mfma_f32_32x32x16_bf16(b0, qr[d0], p0, 0, 0, 0);
;     p1 = __builtin_amdgcn_mfma_f32_32x32x16_bf16(b1, qr[d0], p1, 0, 0, 0); }
; }
	v_mfma_f32_32x32x16_bf16 v[32:47], v[168:171], v[72:75], v[32:47]
	ds_read_b128 v[164:167], v153 offset:49152
	ds_read_b128 v[168:171], v153 offset:57344
	s_waitcnt lgkmcnt(3)
	v_mfma_f32_32x32x16_bf16 v[48:63], v[184:187], v[68:71], v[48:63]
	s_waitcnt lgkmcnt(2)
	v_mfma_f32_32x32x16_bf16 v[32:47], v[188:191], v[68:71], v[32:47]
	s_waitcnt lgkmcnt(1)
	v_mfma_f32_32x32x16_bf16 v[48:63], v[164:167], v[64:67], v[48:63]
	s_waitcnt lgkmcnt(0)
	v_mfma_f32_32x32x16_bf16 v[32:47], v[168:171], v[64:67], v[32:47]
	s_nop 7
	s_nop 4
	v_max_f32_e32 v112, v48, v49
	v_max3_f32 v112, v112, v50, v51
	v_max3_f32 v112, v112, v52, v53
	v_max3_f32 v112, v112, v54, v55
	v_max3_f32 v112, v112, v56, v57
	v_max3_f32 v112, v112, v58, v59
	v_max3_f32 v112, v112, v60, v61
	v_max3_f32 v112, v112, v62, v63
	v_max3_f32 v112, v112, v32, v33
	v_max3_f32 v112, v112, v34, v35
	v_max3_f32 v112, v112, v36, v37
	v_max3_f32 v112, v112, v38, v39
	v_max3_f32 v112, v112, v40, v41
	v_max3_f32 v112, v112, v42, v43
	v_max3_f32 v112, v112, v44, v45
	v_max3_f32 v112, v112, v46, v47
	v_mov_b32_e32 v113, v112
	s_nop 1
	v_permlane32_swap_b32_e32 v112, v113
	v_max_f32_e32 v112, v112, v113
	v_sub_f32_e32 v113, v112, v116
	v_cmp_ge_f32_e32 vcc, s80, v113
	v_max_f32_e32 v112, v116, v112
	v_sub_f32_e32 v113, v116, v112
	v_mul_f32_e32 v113, 0x3e16c740, v113
	v_exp_f32_e32 v113, v113
	s_cmp_eq_u64 vcc, exec
	s_cselect_b64 s[0:1], -1, 0
	v_cndmask_b32_e64 v157, v113, 1.0, s[0:1]
	v_cmp_gt_f32_e32 vcc, 1.0, v157
	v_cndmask_b32_e64 v158, v112, v116, s[0:1]
	v_mul_f32_e32 v159, 0xbe16c740, v158
	v_fmamk_f32 v48, v48, 0x3e16c740, v159
	v_fmamk_f32 v49, v49, 0x3e16c740, v159
	v_fmamk_f32 v50, v50, 0x3e16c740, v159
	v_fmamk_f32 v51, v51, 0x3e16c740, v159
	v_fmamk_f32 v52, v52, 0x3e16c740, v159
	v_fmamk_f32 v53, v53, 0x3e16c740, v159
	v_fmamk_f32 v54, v54, 0x3e16c740, v159
	v_fmamk_f32 v55, v55, 0x3e16c740, v159
	v_fmamk_f32 v56, v56, 0x3e16c740, v159
	v_fmamk_f32 v57, v57, 0x3e16c740, v159
	v_fmamk_f32 v58, v58, 0x3e16c740, v159
	v_fmamk_f32 v59, v59, 0x3e16c740, v159
	v_fmamk_f32 v60, v60, 0x3e16c740, v159
	v_fmamk_f32 v61, v61, 0x3e16c740, v159
	v_fmamk_f32 v62, v62, 0x3e16c740, v159
	v_fmamk_f32 v63, v63, 0x3e16c740, v159
	v_exp_f32_e32 v112, v48
	v_exp_f32_e32 v127, v49
	v_exp_f32_e32 v113, v50
	v_exp_f32_e32 v126, v51
	v_exp_f32_e32 v114, v52
	v_exp_f32_e32 v125, v53
	v_exp_f32_e32 v115, v54
	v_exp_f32_e32 v124, v55
	v_exp_f32_e32 v116, v56
	v_exp_f32_e32 v123, v57
	v_exp_f32_e32 v117, v58
	v_exp_f32_e32 v122, v59
	v_exp_f32_e32 v118, v60
	v_exp_f32_e32 v121, v61
	v_exp_f32_e32 v119, v62
	v_exp_f32_e32 v120, v63
	v_fmamk_f32 v164, v42, 0x3e16c740, v159
	v_fmamk_f32 v165, v43, 0x3e16c740, v159
	v_fmamk_f32 v167, v32, 0x3e16c740, v159
	v_fmamk_f32 v168, v33, 0x3e16c740, v159
	v_fmamk_f32 v169, v34, 0x3e16c740, v159
	v_fmamk_f32 v170, v35, 0x3e16c740, v159
	v_fmamk_f32 v171, v36, 0x3e16c740, v159
	v_fmamk_f32 v172, v37, 0x3e16c740, v159
	v_fmamk_f32 v160, v38, 0x3e16c740, v159
	v_fmamk_f32 v161, v39, 0x3e16c740, v159
	v_fmamk_f32 v162, v40, 0x3e16c740, v159
	v_fmamk_f32 v163, v41, 0x3e16c740, v159
	v_fmamk_f32 v166, v44, 0x3e16c740, v159
	v_fmamk_f32 v173, v45, 0x3e16c740, v159
	v_fmamk_f32 v174, v46, 0x3e16c740, v159
	v_fmac_f32_e32 v159, 0x3e16c740, v47
	s_cbranch_vccz .Lmy_h1B_304
	s_and_saveexec_b64 s[12:13], s[4:5]
	ds_write_b32 v141, v157 offset:128
	s_or_b64 exec, exec, s[12:13]
	s_waitcnt lgkmcnt(0)
	ds_read_b128 v[192:195], v129 offset:224
	ds_read_b128 v[196:199], v129 offset:192
	ds_read_b128 v[200:203], v129 offset:160
	ds_read_b128 v[210:213], v129 offset:128
	s_waitcnt lgkmcnt(3)
	v_pk_mul_f32 v[14:15], v[14:15], v[194:195]
	s_waitcnt lgkmcnt(2)
	v_pk_mul_f32 v[10:11], v[10:11], v[198:199]
	s_waitcnt lgkmcnt(1)
	v_pk_mul_f32 v[6:7], v[6:7], v[202:203]
	s_waitcnt lgkmcnt(0)
	v_pk_mul_f32 v[2:3], v[2:3], v[212:213]
	v_pk_mul_f32 v[12:13], v[12:13], v[192:193]
	v_pk_mul_f32 v[8:9], v[8:9], v[196:197]
	v_pk_mul_f32 v[4:5], v[4:5], v[200:201]
	v_pk_mul_f32 v[0:1], v[0:1], v[210:211]
	v_pk_mul_f32 v[30:31], v[30:31], v[194:195]
	v_pk_mul_f32 v[26:27], v[26:27], v[198:199]
	v_pk_mul_f32 v[22:23], v[22:23], v[202:203]
	v_pk_mul_f32 v[18:19], v[18:19], v[212:213]
	v_pk_mul_f32 v[28:29], v[28:29], v[192:193]
	v_pk_mul_f32 v[24:25], v[24:25], v[196:197]
	v_pk_mul_f32 v[20:21], v[20:21], v[200:201]
	v_pk_mul_f32 v[16:17], v[16:17], v[210:211]
; #define SBAR() __builtin_amdgcn_sched_barrier(0)
; #define SLOAD(i, j) do { const long kr_ = KROW(j); sr_[i].vs0 = ld8(Vp + (kr_ + sr) * ldv + sc); sr_[i].ks0 = ld8(Kp + (kr_ + sr) * ldk + sc); \
;     if (DQK == 96) sr_[i].ks1 = ld8(Kp + (kr_ + sr2) * ldk + sc2); } while (0)
; #define SWRITE(b, i) do { *(bf16x8*)(V_lds + (b) * SHM_V + vst0) = sr_[i].vs0; *(bf16x8*)(K_lds + (b) * SHM_K + kst0) = sr_[i].ks0; \
;     if (DQK == 96) *(bf16x8*)(K_lds + (b) * SHM_K + kst1) = sr_[i].ks1; } while (0)
; #define RESC(a) do { if (__any((a) < 1.f)) { if (hi == 0) al_l[r32] = (a); asm volatile("s_waitcnt lgkmcnt(0)" ::: "memory"); \
;     _Pragma("unroll") for (int d = 0; d < 2; ++d) _Pragma("unroll") for (int r = 0; r < 16; ++r) o[d][r] *= al_l[crow(r, hi)]; } } while (0)
; __device__ __forceinline__ void finishSM(f32x16& p0, f32x16& p1, float alpha, float& l_reg, bf16x8& pa0, bf16x8& pa1, bf16x8& pa2, bf16x8& pa3) {
; #pragma unroll
;   for (int r = 0; r < 16; ++r) p1[r] = __builtin_amdgcn_exp2f(p1[r]);
;   float ps = 0;
; #pragma unroll
;   for (int r = 0; r < 16; ++r) ps += p0[r];
; #pragma unroll
;   for (int r = 0; r < 16; ++r) ps += p1[r];
;   { auto rr = __builtin_amdgcn_permlane32_swap(__float_as_uint(ps), __float_as_uint(ps), false, false);
;     ps = __uint_as_float(rr[0]) + __uint_as_float(rr[1]); }
;   l_reg = l_reg * alpha + ps;
;     ...
;   PK4(p0, 0, pa0); PK4(p0, 8, pa1); PK4(p1, 0, pa2); PK4(p1, 8, pa3);
;     ...
; }
; template <int DQK, int MODE, int ldq, int ldk, int ldv> ...
;     ...
;     __syncthreads(); SWRITE(0, SE);
;     RESC(alB); __syncthreads();
;     SBAR(); qkt<DQK>(pA0, pA1, K_lds, qr, r32, hi);
;     finishSM(pB0, pB1, alB, l_reg, pa0, pa1, pa2, pa3); SBAR();
;     if (j + 3 < NT) SLOAD(SE, j + 3); SBAR();
.Lmy_h1B_304:
	s_waitcnt lgkmcnt(0)
	s_barrier
	s_waitcnt vmcnt(0)
	ds_write_b128 v146, v[100:103] offset:49152
	ds_write_b128 v145, v[108:111]
	v_exp_f32_e32 v175, v164
	v_add_f32_e32 v164, 0, v112
	v_add_f32_e32 v164, v127, v164
	v_add_f32_e32 v164, v113, v164
	v_add_f32_e32 v164, v126, v164
	v_add_f32_e32 v164, v114, v164
	v_add_f32_e32 v164, v125, v164
	v_add_f32_e32 v164, v115, v164
	v_add_f32_e32 v164, v124, v164
	v_add_f32_e32 v164, v116, v164
	v_add_f32_e32 v164, v123, v164
	v_add_f32_e32 v164, v117, v164
	v_add_f32_e32 v164, v122, v164
	v_exp_f32_e32 v167, v167
	v_add_f32_e32 v164, v118, v164
	v_exp_f32_e32 v168, v168
	v_add_f32_e32 v164, v121, v164
	v_exp_f32_e32 v169, v169
	v_add_f32_e32 v164, v119, v164
	v_exp_f32_e32 v170, v170
	v_add_f32_e32 v164, v120, v164
	v_exp_f32_e32 v171, v171
	v_add_f32_e32 v164, v167, v164
	v_exp_f32_e32 v172, v172
	v_add_f32_e32 v164, v168, v164
	v_exp_f32_e32 v160, v160
	v_add_f32_e32 v164, v169, v164
	v_exp_f32_e32 v161, v161
	v_add_f32_e32 v164, v170, v164
	v_exp_f32_e32 v162, v162
	v_add_f32_e32 v164, v171, v164
	v_exp_f32_e32 v163, v163
	v_add_f32_e32 v164, v172, v164
	v_add_f32_e32 v164, v160, v164
	v_add_f32_e32 v164, v161, v164
	v_exp_f32_e32 v166, v166
	v_add_f32_e32 v164, v162, v164
	v_exp_f32_e32 v173, v173
	v_add_f32_e32 v164, v163, v164
	v_exp_f32_e32 v174, v174
	v_add_f32_e32 v164, v175, v164
	v_exp_f32_e32 v159, v159
	v_cvt_pk_bf16_f32 v214, v112, v127
	v_cvt_pk_bf16_f32 v215, v113, v126
	v_cvt_pk_bf16_f32 v216, v114, v125
	v_cvt_pk_bf16_f32 v217, v115, v124
	v_cvt_pk_bf16_f32 v218, v116, v123
	v_cvt_pk_bf16_f32 v219, v117, v122
	v_exp_f32_e32 v176, v165
	v_cvt_pk_bf16_f32 v220, v118, v121
	v_cvt_pk_bf16_f32 v221, v119, v120
	v_cvt_pk_bf16_f32 v222, v167, v168
	v_cvt_pk_bf16_f32 v223, v169, v170
	v_cvt_pk_bf16_f32 v224, v171, v172
	s_nop 0
	v_add_f32_e32 v164, v176, v164
	v_add_f32_e32 v164, v166, v164
	v_add_f32_e32 v164, v173, v164
	v_add_f32_e32 v164, v174, v164
	v_add_f32_e32 v164, v159, v164
	v_mov_b32_e32 v165, v164
	v_cvt_pk_bf16_f32 v225, v160, v161
	v_cvt_pk_bf16_f32 v226, v162, v163
	v_cvt_pk_bf16_f32 v227, v175, v176
	v_cvt_pk_bf16_f32 v228, v166, v173
	v_cvt_pk_bf16_f32 v229, v174, v159
	s_nop 1
	v_permlane32_swap_b32_e32 v164, v165
	v_permlane32_swap_b32_e32 v214, v216
	v_permlane32_swap_b32_e32 v215, v217
	v_permlane32_swap_b32_e32 v218, v220
	v_permlane32_swap_b32_e32 v219, v221
	v_permlane32_swap_b32_e32 v222, v224
	v_permlane32_swap_b32_e32 v223, v225
	v_permlane32_swap_b32_e32 v226, v228
	v_permlane32_swap_b32_e32 v227, v229
	s_cmpk_lt_u32 s25, 0x7e
	s_cselect_b32 s98, 0, 0xffffff80
	s_cselect_b32 s99, s10, s24
	s_add_i32 s98, s98, s11
	s_lshl_b32 s98, s98, 6
	s_add_i32 s98, s98, s99
	s_sub_i32 s98, s98, 64
	s_ashr_i32 s99, s98, 31
	s_lshl_b32 s98, s98, 9
	s_add_u32 s98, s20, s98
	s_addc_u32 s99, s21, 0
	global_load_dwordx4 v[92:95], v231, s[98:99]
	s_cmpk_gt_u32 s25, 0x80
	s_cbranch_scc1 .Lmy_h2B_306
	s_cmpk_lt_u32 s25, 0x7d
	s_cselect_b32 s0, 0, 0xffffff80
	s_cselect_b32 s1, s10, s24
	s_add_i32 s0, s0, s11
	s_lshl_b32 s0, s0, 6
	s_add_i32 s0, s0, s1
	s_ashr_i32 s1, s0, 31
	s_mul_i32 s1, s0, 0x300
	s_add_u32 s12, s18, s1
	s_addc_u32 s13, s19, 0
	global_load_dwordx4 v[88:91], v230, s[12:13]
; template <int DQK> __device__ __forceinline__ void partialSM(f32x16& p0, f32x16& p1, float& m_reg, float& mn, float& alpha) {
;   constexpr float SCALE = (DQK == 96) ? 0.10206207261596577f : 0.125f;
;   constexpr float C = SCALE * 1.4426950408889634f;
;   float pmax = p0[0];
; #pragma unroll
;   for (int r = 1; r < 16; ++r) pmax = fmaxf(pmax, p0[r]);
; #pragma unroll
;   for (int r = 0; r < 16; ++r) pmax = fmaxf(pmax, p1[r]);
;   { auto rr = __builtin_amdgcn_permlane32_swap(__float_as_uint(pmax), __float_as_uint(pmax), false, false);
;     pmax = fmaxf(__uint_as_float(rr[0]), __uint_as_float(rr[1])); }
;   if (__builtin_expect(__all(pmax - m_reg <= THR / SCALE), 1)) { mn = m_reg; alpha = 1.f; }
;   else { mn = fmaxf(m_reg, pmax); alpha = __builtin_amdgcn_exp2f((m_reg - mn) * C); m_reg = mn; }
;   float mnC = -mn * C;
; #pragma unroll
;   for (int r = 0; r < 16; ++r) p0[r] = fmaf(p0[r], C, mnC);
; #pragma unroll
;   for (int r = 0; r < 16; ++r) p1[r] = fmaf(p1[r], C, mnC);
; #pragma unroll
;   for (int r = 0; r < 16; ++r) p0[r] = __builtin_amdgcn_exp2f(p0[r]);
; }
; template <int DQK> __device__ __forceinline__ void qkt(f32x16& p0, f32x16& p1, const char* Ks, const bf16x8* qr, int r32, int hi) {
;   p0 = f32x16{}; p1 = f32x16{};
; #pragma unroll
;   for (int d0 = 0; d0 < DQK / 16; ++d0) { int cb = (d0 * 16 + hi * 8) * 2;
;     bf16x8 b0 = *reinterpret_cast<const bf16x8*>(Ks + KSWZ(r32, cb));
;     bf16x8 b1 = *reinterpret_cast<const bf16x8*>(Ks + KSWZ(32 + r32, cb));
;     p0 = __builtin_amdgcn_mfma_f32_32x32x16_bf16(b0, qr[d0], p0, 0, 0, 0);
;     p1 = __builtin_amdgcn_mfma_f32_32x32x16_bf16(b1, qr[d0], p1, 0, 0, 0); }
; }
; __device__ __forceinline__ int v_st(int k, int c) { const int kk = (k & ~0xC) | ((k & 4) << 1) | ((k & 8) >> 1); return ((kk >> 3) * 4 + (c >> 5)) * 512 + ((kk & 7) * 32 + (c & 31)) * 2; }
; __device__ __forceinline__ int v_rd_base(int lane) { return ((lane & 3) << 3) | (((lane >> 2) & 3) << 6) | (((lane >> 4) & 1) << 5) | (((lane >> 5) & 1) << 8); }
; template <int OFF> __device__ __forceinline__ s16x4 tr_read(int vb) {
;   s16x4 r; asm volatile("ds_read_b64_tr_b16 %0, %1 offset:%2" : "=&v"(r) : "v"(vb), "i"(OFF) : "memory"); return r;
; }
; template <int D0> __device__ __forceinline__ void pv_one(f32x16& od, int vb, bf16x8 pa0, bf16x8 pa1, bf16x8 pa2, bf16x8 pa3) {
.Lmy_h2B_306:
	ds_read_b64_tr_b16 v[192:193], v143 offset:0
	ds_read_b64_tr_b16 v[194:195], v143 offset:0x800
	ds_read_b64_tr_b16 v[196:197], v143 offset:0x1000
	ds_read_b64_tr_b16 v[198:199], v143 offset:0x1800
	ds_read_b64_tr_b16 v[200:201], v143 offset:0x2000
	ds_read_b64_tr_b16 v[202:203], v143 offset:0x2800
	ds_read_b64_tr_b16 v[210:211], v143 offset:0x3000
	ds_read_b64_tr_b16 v[212:213], v143 offset:0x3800
	s_waitcnt lgkmcnt(0)
	s_nop 0
	v_mfma_f32_32x32x16_bf16 v[0:15], v[214:217], v[192:195], v[0:15]
	ds_read_b64_tr_b16 v[192:193], v143 offset:0x200
	ds_read_b64_tr_b16 v[194:195], v143 offset:0xa00
	v_mfma_f32_32x32x16_bf16 v[0:15], v[218:221], v[196:199], v[0:15]
	ds_read_b64_tr_b16 v[196:197], v143 offset:0x1200
	ds_read_b64_tr_b16 v[198:199], v143 offset:0x1a00
	v_mfma_f32_32x32x16_bf16 v[0:15], v[222:225], v[200:203], v[0:15]
	ds_read_b64_tr_b16 v[200:201], v143 offset:0x2200
	ds_read_b64_tr_b16 v[202:203], v143 offset:0x2a00
	v_mfma_f32_32x32x16_bf16 v[0:15], v[226:229], v[210:213], v[0:15]
	ds_read_b64_tr_b16 v[210:211], v143 offset:0x3200
	ds_read_b64_tr_b16 v[212:213], v143 offset:0x3a00
	s_waitcnt lgkmcnt(0)
	v_mfma_f32_32x32x16_bf16 v[16:31], v[214:217], v[192:195], v[16:31]
	v_mfma_f32_32x32x16_bf16 v[16:31], v[218:221], v[196:199], v[16:31]
	v_mfma_f32_32x32x16_bf16 v[16:31], v[222:225], v[200:203], v[16:31]
	v_mfma_f32_32x32x16_bf16 v[16:31], v[226:229], v[210:213], v[16:31]
	ds_read_b128 v[32:35], v148 offset:32768
	ds_read_b128 v[36:39], v148 offset:40960
	ds_read_b128 v[176:179], v152 offset:32768
	ds_read_b128 v[180:183], v152 offset:40960
	ds_read_b128 v[184:187], v151 offset:32768
	ds_read_b128 v[188:191], v151 offset:40960
	s_waitcnt lgkmcnt(5)
	v_mfma_f32_32x32x16_bf16 v[48:63], v[32:35], v[84:87], 0
	s_waitcnt lgkmcnt(4)
	v_mfma_f32_32x32x16_bf16 v[32:47], v[36:39], v[84:87], 0
	s_waitcnt lgkmcnt(3)
	v_mfma_f32_32x32x16_bf16 v[48:63], v[176:179], v[80:83], v[48:63]
	s_waitcnt lgkmcnt(2)
	v_mfma_f32_32x32x16_bf16 v[32:47], v[180:183], v[80:83], v[32:47]
	ds_read_b128 v[176:179], v149 offset:32768
	ds_read_b128 v[180:183], v149 offset:40960
	s_waitcnt lgkmcnt(3)
	v_mfma_f32_32x32x16_bf16 v[48:63], v[184:187], v[76:79], v[48:63]
	s_waitcnt lgkmcnt(2)
	v_mfma_f32_32x32x16_bf16 v[32:47], v[188:191], v[76:79], v[32:47]
	ds_read_b128 v[184:187], v150 offset:32768
	ds_read_b128 v[188:191], v150 offset:40960
	s_waitcnt lgkmcnt(3)
	v_mfma_f32_32x32x16_bf16 v[48:63], v[176:179], v[72:75], v[48:63]
	s_waitcnt lgkmcnt(2)
	v_mfma_f32_32x32x16_bf16 v[32:47], v[180:183], v[72:75], v[32:47]
	ds_read_b128 v[176:179], v153 offset:32768
	ds_read_b128 v[180:183], v153 offset:40960
	s_waitcnt lgkmcnt(3)
	v_mfma_f32_32x32x16_bf16 v[48:63], v[184:187], v[68:71], v[48:63]
	s_waitcnt lgkmcnt(2)
	v_mfma_f32_32x32x16_bf16 v[32:47], v[188:191], v[68:71], v[32:47]
	s_waitcnt lgkmcnt(1)
	v_mfma_f32_32x32x16_bf16 v[48:63], v[176:179], v[64:67], v[48:63]
	s_waitcnt lgkmcnt(0)
	v_mfma_f32_32x32x16_bf16 v[32:47], v[180:183], v[64:67], v[32:47]
	s_nop 7
	s_nop 4
	v_max_f32_e32 v112, v48, v49
	v_max3_f32 v112, v112, v50, v51
	v_max3_f32 v112, v112, v52, v53
	v_max3_f32 v112, v112, v54, v55
	v_max3_f32 v112, v112, v56, v57
	v_max3_f32 v112, v112, v58, v59
	v_max3_f32 v112, v112, v60, v61
	v_max3_f32 v112, v112, v62, v63
	v_max3_f32 v112, v112, v32, v33
	v_max3_f32 v112, v112, v34, v35
	v_max3_f32 v112, v112, v36, v37
	v_max3_f32 v112, v112, v38, v39
	v_max3_f32 v112, v112, v40, v41
	v_max3_f32 v112, v112, v42, v43
	v_max3_f32 v112, v112, v44, v45
	v_max3_f32 v112, v112, v46, v47
	v_mov_b32_e32 v113, v112
	s_nop 1
	v_permlane32_swap_b32_e32 v112, v113
	v_max_f32_e32 v112, v112, v113
	v_sub_f32_e32 v113, v112, v158
	v_cmp_ge_f32_e32 vcc, s80, v113
	v_max_f32_e32 v112, v158, v112
	v_sub_f32_e32 v113, v158, v112
	v_mul_f32_e32 v113, 0x3e16c740, v113
	v_exp_f32_e32 v113, v113
	s_cmp_eq_u64 vcc, exec
	s_cselect_b64 s[0:1], -1, 0
	v_cndmask_b32_e64 v117, v113, 1.0, s[0:1]
	v_cmp_gt_f32_e32 vcc, 1.0, v117
	v_cndmask_b32_e64 v116, v112, v158, s[0:1]
	v_mul_f32_e32 v100, 0xbe16c740, v116
	v_mov_b32_e32 v101, v100
	v_fmamk_f32 v48, v48, 0x3e16c740, v100
	v_fmamk_f32 v49, v49, 0x3e16c740, v100
	v_fmamk_f32 v50, v50, 0x3e16c740, v100
	v_fmamk_f32 v51, v51, 0x3e16c740, v100
	v_fmamk_f32 v52, v52, 0x3e16c740, v100
	v_fmamk_f32 v53, v53, 0x3e16c740, v100
	v_fmamk_f32 v54, v54, 0x3e16c740, v100
	v_fmamk_f32 v55, v55, 0x3e16c740, v100
	v_fmamk_f32 v56, v56, 0x3e16c740, v100
	v_fmamk_f32 v57, v57, 0x3e16c740, v100
	v_fmamk_f32 v58, v58, 0x3e16c740, v100
	v_fmamk_f32 v59, v59, 0x3e16c740, v100
	v_fmamk_f32 v60, v60, 0x3e16c740, v100
	v_fmamk_f32 v61, v61, 0x3e16c740, v100
	v_fmamk_f32 v62, v62, 0x3e16c740, v100
	v_fmac_f32_e32 v101, 0x3e16c740, v63
	v_exp_f32_e32 v126, v48
	v_exp_f32_e32 v160, v49
	v_exp_f32_e32 v127, v50
	v_exp_f32_e32 v161, v51
	v_exp_f32_e32 v158, v52
	v_exp_f32_e32 v162, v53
	v_exp_f32_e32 v159, v54
	v_exp_f32_e32 v163, v55
	v_exp_f32_e32 v118, v56
	v_exp_f32_e32 v121, v57
	v_exp_f32_e32 v119, v58
	v_exp_f32_e32 v122, v59
	v_exp_f32_e32 v120, v60
	v_exp_f32_e32 v123, v61
	v_exp_f32_e32 v124, v62
	v_exp_f32_e32 v125, v101
	v_pk_fma_f32 v[114:115], v[32:33], s[40:41], v[100:101] op_sel_hi:[1,0,0]
	v_add_f32_e32 v32, v155, v156
	v_fmac_f32_e32 v32, v154, v142
	v_add_f32_e32 v142, v164, v165
	v_pk_fma_f32 v[112:113], v[34:35], s[40:41], v[100:101] op_sel_hi:[1,0,0]
	v_pk_fma_f32 v[108:109], v[36:37], s[40:41], v[100:101] op_sel_hi:[1,0,0]
	v_pk_fma_f32 v[104:105], v[38:39], s[40:41], v[100:101] op_sel_hi:[1,0,0]
	v_pk_fma_f32 v[102:103], v[40:41], s[40:41], v[100:101] op_sel_hi:[1,0,0]
	v_pk_fma_f32 v[110:111], v[42:43], s[40:41], v[100:101] op_sel_hi:[1,0,0]
	v_pk_fma_f32 v[106:107], v[44:45], s[40:41], v[100:101] op_sel_hi:[1,0,0]
	v_pk_fma_f32 v[100:101], v[46:47], s[40:41], v[100:101] op_sel_hi:[1,0,0]
	v_fmac_f32_e32 v142, v32, v157
	s_cbranch_vccz .Lmy_h2B_310
	s_and_saveexec_b64 s[12:13], s[4:5]
	ds_write_b32 v141, v117 offset:128
	s_or_b64 exec, exec, s[12:13]
	s_waitcnt lgkmcnt(0)
	ds_read_b128 v[192:195], v129 offset:224
	ds_read_b128 v[196:199], v129 offset:192
	ds_read_b128 v[200:203], v129 offset:160
	ds_read_b128 v[210:213], v129 offset:128
	s_waitcnt lgkmcnt(3)
	v_pk_mul_f32 v[14:15], v[14:15], v[194:195]
	s_waitcnt lgkmcnt(2)
	v_pk_mul_f32 v[10:11], v[10:11], v[198:199]
	s_waitcnt lgkmcnt(1)
	v_pk_mul_f32 v[6:7], v[6:7], v[202:203]
	s_waitcnt lgkmcnt(0)
	v_pk_mul_f32 v[2:3], v[2:3], v[212:213]
	v_pk_mul_f32 v[12:13], v[12:13], v[192:193]
	v_pk_mul_f32 v[8:9], v[8:9], v[196:197]
	v_pk_mul_f32 v[4:5], v[4:5], v[200:201]
	v_pk_mul_f32 v[0:1], v[0:1], v[210:211]
	v_pk_mul_f32 v[30:31], v[30:31], v[194:195]
	v_pk_mul_f32 v[26:27], v[26:27], v[198:199]
	v_pk_mul_f32 v[22:23], v[22:23], v[202:203]
	v_pk_mul_f32 v[18:19], v[18:19], v[212:213]
	v_pk_mul_f32 v[28:29], v[28:29], v[192:193]
	v_pk_mul_f32 v[24:25], v[24:25], v[196:197]
	v_pk_mul_f32 v[20:21], v[20:21], v[200:201]
	v_pk_mul_f32 v[16:17], v[16:17], v[210:211]
